# GEMM MFMA blocks: priority dropped momentarily every 4 MFMAs so the partner wave's loader can issue
# baseline (speedup 1.0000x reference)
.LBB0_538:
	ds_read_b128 v[152:155], v149
	ds_read_b128 v[156:159], v149 offset:1024
	ds_read_b128 v[160:163], v149 offset:2048
	ds_read_b128 v[164:167], v149 offset:3072
	ds_read_b128 v[168:171], v150
	ds_read_b128 v[172:175], v150 offset:1024
	ds_read_b128 v[176:179], v150 offset:2048
	ds_read_b128 v[180:183], v150 offset:3072
	s_add_u32 s40, s38, 0xfffc0080
	s_addc_u32 s41, s39, -1
	s_cmp_eq_u32 s54, 12
	s_cselect_b32 s43, s27, s41
	s_cselect_b32 s42, s50, s40
	s_cselect_b32 s41, s25, s53
	s_cselect_b32 s40, s51, s52
	v_lshl_add_u64 v[144:145], s[38:39], 0, v[136:137]
	s_add_i32 m0, s11, 0xc000
	ds_read_b128 v[184:187], v151
	ds_read_b128 v[188:191], v151 offset:1024
	ds_read_b128 v[192:195], v151 offset:2048
	ds_read_b128 v[196:199], v151 offset:3072
	ds_read_b128 v[200:203], v151 offset:4096
	ds_read_b128 v[204:207], v151 offset:5120
	ds_read_b128 v[212:215], v151 offset:6144
	ds_read_b128 v[216:219], v151 offset:7168
	global_load_lds_dwordx4 v[144:145], off
	v_lshl_add_u64 v[144:145], s[38:39], 0, v[138:139]
	s_add_i32 m0, s11, 0xe000
	s_nop 0
	global_load_lds_dwordx4 v[144:145], off
	s_waitcnt vmcnt(8)
	s_waitcnt lgkmcnt(0)
	s_barrier
	s_setprio 1
	s_waitcnt lgkmcnt(0)
	v_mfma_f32_16x16x32_bf16 v[124:127], v[152:155], v[184:187], v[124:127]
	v_mfma_f32_16x16x32_bf16 v[120:123], v[160:163], v[184:187], v[120:123]
	v_mfma_f32_16x16x32_bf16 v[108:111], v[152:155], v[192:195], v[108:111]
	v_mfma_f32_16x16x32_bf16 v[104:107], v[160:163], v[192:195], v[104:107]
	s_setprio 0
	s_setprio 1
	v_mfma_f32_16x16x32_bf16 v[92:95], v[152:155], v[200:203], v[92:95]
	v_mfma_f32_16x16x32_bf16 v[88:91], v[160:163], v[200:203], v[88:91]
	v_mfma_f32_16x16x32_bf16 v[76:79], v[152:155], v[212:215], v[76:79]
	v_mfma_f32_16x16x32_bf16 v[72:75], v[160:163], v[212:215], v[72:75]
	s_setprio 0
	s_setprio 1
	v_mfma_f32_16x16x32_bf16 v[124:127], v[156:159], v[188:191], v[124:127]
	v_mfma_f32_16x16x32_bf16 v[120:123], v[164:167], v[188:191], v[120:123]
	v_mfma_f32_16x16x32_bf16 v[108:111], v[156:159], v[196:199], v[108:111]
	v_mfma_f32_16x16x32_bf16 v[104:107], v[164:167], v[196:199], v[104:107]
	s_setprio 0
	s_setprio 1
	v_mfma_f32_16x16x32_bf16 v[92:95], v[156:159], v[204:207], v[92:95]
	v_mfma_f32_16x16x32_bf16 v[88:91], v[164:167], v[204:207], v[88:91]
	v_mfma_f32_16x16x32_bf16 v[76:79], v[156:159], v[216:219], v[76:79]
	v_mfma_f32_16x16x32_bf16 v[72:75], v[164:167], v[216:219], v[72:75]
	s_setprio 0
	s_setprio 1
	v_mfma_f32_16x16x32_bf16 v[116:119], v[168:171], v[184:187], v[116:119]
	v_mfma_f32_16x16x32_bf16 v[112:115], v[176:179], v[184:187], v[112:115]
	v_mfma_f32_16x16x32_bf16 v[100:103], v[168:171], v[192:195], v[100:103]
	v_mfma_f32_16x16x32_bf16 v[96:99], v[176:179], v[192:195], v[96:99]
	s_setprio 0
	s_setprio 1
	v_mfma_f32_16x16x32_bf16 v[84:87], v[168:171], v[200:203], v[84:87]
	v_mfma_f32_16x16x32_bf16 v[80:83], v[176:179], v[200:203], v[80:83]
	v_mfma_f32_16x16x32_bf16 v[68:71], v[168:171], v[212:215], v[68:71]
	v_mfma_f32_16x16x32_bf16 v[64:67], v[176:179], v[212:215], v[64:67]
	s_setprio 0
	s_setprio 1
	v_mfma_f32_16x16x32_bf16 v[116:119], v[172:175], v[188:191], v[116:119]
	v_mfma_f32_16x16x32_bf16 v[112:115], v[180:183], v[188:191], v[112:115]
	v_mfma_f32_16x16x32_bf16 v[100:103], v[172:175], v[196:199], v[100:103]
	v_mfma_f32_16x16x32_bf16 v[96:99], v[180:183], v[196:199], v[96:99]
	s_setprio 0
	s_setprio 1
	v_mfma_f32_16x16x32_bf16 v[84:87], v[172:175], v[204:207], v[84:87]
	v_mfma_f32_16x16x32_bf16 v[80:83], v[180:183], v[204:207], v[80:83]
	v_mfma_f32_16x16x32_bf16 v[68:71], v[172:175], v[216:219], v[68:71]
	v_mfma_f32_16x16x32_bf16 v[64:67], v[180:183], v[216:219], v[64:67]
	s_setprio 0
	s_barrier
	s_add_i32 s55, s45, s10
	v_lshl_add_u64 v[144:145], s[40:41], 0, v[132:133]
	s_mov_b32 m0, s55
	ds_read_b128 v[184:187], v151 offset:16384
	ds_read_b128 v[188:191], v151 offset:17408
	ds_read_b128 v[192:195], v151 offset:18432
	ds_read_b128 v[196:199], v151 offset:19456
	ds_read_b128 v[200:203], v151 offset:20480
	ds_read_b128 v[204:207], v151 offset:21504
	ds_read_b128 v[212:215], v151 offset:22528
	ds_read_b128 v[216:219], v151 offset:23552
	global_load_lds_dwordx4 v[144:145], off
	s_add_i32 m0, s55, 0x2000
	s_add_u32 s56, s40, 0x40000
	v_lshl_add_u64 v[208:209], s[40:41], 0, v[128:129]
	s_addc_u32 s57, s41, 0
	s_add_i32 s55, s46, s10
	global_load_lds_dwordx4 v[208:209], off
	v_lshl_add_u64 v[220:221], s[56:57], 0, v[132:133]
	s_mov_b32 m0, s55
	v_lshl_add_u64 v[222:223], s[42:43], 0, v[130:131]
	global_load_lds_dwordx4 v[220:221], off
	v_lshl_add_u64 v[220:221], s[56:57], 0, v[128:129]
	s_add_i32 m0, s55, 0x2000
	s_nop 0
	global_load_lds_dwordx4 v[220:221], off
	v_lshl_add_u64 v[220:221], s[42:43], 0, v[134:135]
	s_mov_b32 m0, s11
	s_nop 0
	global_load_lds_dwordx4 v[220:221], off
	s_mov_b32 m0, s14
	s_nop 0
	global_load_lds_dwordx4 v[222:223], off
	s_waitcnt vmcnt(8)
	s_waitcnt lgkmcnt(0)
	s_barrier
	s_setprio 1
	s_waitcnt lgkmcnt(0)
	v_mfma_f32_16x16x32_bf16 v[60:63], v[152:155], v[184:187], v[60:63]
	v_mfma_f32_16x16x32_bf16 v[56:59], v[160:163], v[184:187], v[56:59]
	v_mfma_f32_16x16x32_bf16 v[44:47], v[152:155], v[192:195], v[44:47]
	v_mfma_f32_16x16x32_bf16 v[40:43], v[160:163], v[192:195], v[40:43]
	s_setprio 0
	s_setprio 1
	v_mfma_f32_16x16x32_bf16 v[28:31], v[152:155], v[200:203], v[28:31]
	v_mfma_f32_16x16x32_bf16 v[24:27], v[160:163], v[200:203], v[24:27]
	v_mfma_f32_16x16x32_bf16 v[12:15], v[152:155], v[212:215], v[12:15]
	v_mfma_f32_16x16x32_bf16 v[8:11], v[160:163], v[212:215], v[8:11]
	s_setprio 0
	s_setprio 1
	v_mfma_f32_16x16x32_bf16 v[60:63], v[156:159], v[188:191], v[60:63]
	v_mfma_f32_16x16x32_bf16 v[56:59], v[164:167], v[188:191], v[56:59]
	v_mfma_f32_16x16x32_bf16 v[44:47], v[156:159], v[196:199], v[44:47]
	v_mfma_f32_16x16x32_bf16 v[40:43], v[164:167], v[196:199], v[40:43]
	s_setprio 0
	s_setprio 1
	v_mfma_f32_16x16x32_bf16 v[28:31], v[156:159], v[204:207], v[28:31]
	v_mfma_f32_16x16x32_bf16 v[24:27], v[164:167], v[204:207], v[24:27]
	v_mfma_f32_16x16x32_bf16 v[12:15], v[156:159], v[216:219], v[12:15]
	v_mfma_f32_16x16x32_bf16 v[8:11], v[164:167], v[216:219], v[8:11]
	s_setprio 0
	s_setprio 1
	v_mfma_f32_16x16x32_bf16 v[52:55], v[168:171], v[184:187], v[52:55]
	v_mfma_f32_16x16x32_bf16 v[48:51], v[176:179], v[184:187], v[48:51]
	v_mfma_f32_16x16x32_bf16 v[36:39], v[168:171], v[192:195], v[36:39]
	v_mfma_f32_16x16x32_bf16 v[32:35], v[176:179], v[192:195], v[32:35]
	s_setprio 0
	s_setprio 1
	v_mfma_f32_16x16x32_bf16 v[20:23], v[168:171], v[200:203], v[20:23]
	v_mfma_f32_16x16x32_bf16 v[16:19], v[176:179], v[200:203], v[16:19]
	v_mfma_f32_16x16x32_bf16 v[4:7], v[168:171], v[212:215], v[4:7]
	v_mfma_f32_16x16x32_bf16 v[0:3], v[176:179], v[212:215], v[0:3]
	s_setprio 0
	s_setprio 1
	v_mfma_f32_16x16x32_bf16 v[52:55], v[172:175], v[188:191], v[52:55]
	v_mfma_f32_16x16x32_bf16 v[48:51], v[180:183], v[188:191], v[48:51]
	v_mfma_f32_16x16x32_bf16 v[36:39], v[172:175], v[196:199], v[36:39]
	v_mfma_f32_16x16x32_bf16 v[32:35], v[180:183], v[196:199], v[32:35]
	s_setprio 0
	s_setprio 1
	v_mfma_f32_16x16x32_bf16 v[20:23], v[172:175], v[204:207], v[20:23]
	v_mfma_f32_16x16x32_bf16 v[16:19], v[180:183], v[204:207], v[16:19]
	v_mfma_f32_16x16x32_bf16 v[4:7], v[172:175], v[216:219], v[4:7]
	v_mfma_f32_16x16x32_bf16 v[0:3], v[180:183], v[216:219], v[0:3]
	s_setprio 0
	s_barrier
	s_add_i32 s55, 0, 0x18000
	s_add_i32 s56, 0, 0x1c000
	v_add_u32_e32 v164, s55, v147
	v_add_u32_e32 v180, s56, v147
	ds_read_b128 v[152:155], v164
	ds_read_b128 v[156:159], v164 offset:1024
	ds_read_b128 v[160:163], v164 offset:2048
	ds_read_b128 v[164:167], v164 offset:3072
	ds_read_b128 v[168:171], v180
	ds_read_b128 v[172:175], v180 offset:1024
	ds_read_b128 v[176:179], v180 offset:2048
	ds_read_b128 v[180:183], v180 offset:3072
	s_add_u32 s42, s42, 0x40000
	s_addc_u32 s43, s43, 0
	s_mov_b32 m0, s15
	v_lshl_add_u64 v[224:225], s[42:43], 0, v[134:135]
	ds_read_b128 v[184:187], v151 offset:32768
	ds_read_b128 v[188:191], v151 offset:33792
	ds_read_b128 v[192:195], v151 offset:34816
	ds_read_b128 v[196:199], v151 offset:35840
	ds_read_b128 v[200:203], v151 offset:36864
	ds_read_b128 v[204:207], v151 offset:37888
	ds_read_b128 v[212:215], v151 offset:38912
	ds_read_b128 v[216:219], v151 offset:39936
	global_load_lds_dwordx4 v[224:225], off
	v_lshl_add_u64 v[224:225], s[42:43], 0, v[130:131]
	s_mov_b32 m0, s28
	s_nop 0
	global_load_lds_dwordx4 v[224:225], off
	s_waitcnt vmcnt(8)
	s_waitcnt lgkmcnt(0)
	s_barrier
	s_setprio 1
	s_waitcnt lgkmcnt(0)
	v_mfma_f32_16x16x32_bf16 v[124:127], v[152:155], v[184:187], v[124:127]
	v_mfma_f32_16x16x32_bf16 v[120:123], v[160:163], v[184:187], v[120:123]
	v_mfma_f32_16x16x32_bf16 v[108:111], v[152:155], v[192:195], v[108:111]
	v_mfma_f32_16x16x32_bf16 v[104:107], v[160:163], v[192:195], v[104:107]
	s_setprio 0
	s_setprio 1
	v_mfma_f32_16x16x32_bf16 v[92:95], v[152:155], v[200:203], v[92:95]
	v_mfma_f32_16x16x32_bf16 v[88:91], v[160:163], v[200:203], v[88:91]
	v_mfma_f32_16x16x32_bf16 v[76:79], v[152:155], v[212:215], v[76:79]
	v_mfma_f32_16x16x32_bf16 v[72:75], v[160:163], v[212:215], v[72:75]
	s_setprio 0
	s_setprio 1
	v_mfma_f32_16x16x32_bf16 v[124:127], v[156:159], v[188:191], v[124:127]
	v_mfma_f32_16x16x32_bf16 v[120:123], v[164:167], v[188:191], v[120:123]
	v_mfma_f32_16x16x32_bf16 v[108:111], v[156:159], v[196:199], v[108:111]
	v_mfma_f32_16x16x32_bf16 v[104:107], v[164:167], v[196:199], v[104:107]
	s_setprio 0
	s_setprio 1
	v_mfma_f32_16x16x32_bf16 v[92:95], v[156:159], v[204:207], v[92:95]
	v_mfma_f32_16x16x32_bf16 v[88:91], v[164:167], v[204:207], v[88:91]
	v_mfma_f32_16x16x32_bf16 v[76:79], v[156:159], v[216:219], v[76:79]
	v_mfma_f32_16x16x32_bf16 v[72:75], v[164:167], v[216:219], v[72:75]
	s_setprio 0
	s_setprio 1
	v_mfma_f32_16x16x32_bf16 v[116:119], v[168:171], v[184:187], v[116:119]
	v_mfma_f32_16x16x32_bf16 v[112:115], v[176:179], v[184:187], v[112:115]
	v_mfma_f32_16x16x32_bf16 v[100:103], v[168:171], v[192:195], v[100:103]
	v_mfma_f32_16x16x32_bf16 v[96:99], v[176:179], v[192:195], v[96:99]
	s_setprio 0
	s_setprio 1
	v_mfma_f32_16x16x32_bf16 v[84:87], v[168:171], v[200:203], v[84:87]
	v_mfma_f32_16x16x32_bf16 v[80:83], v[176:179], v[200:203], v[80:83]
	v_mfma_f32_16x16x32_bf16 v[68:71], v[168:171], v[212:215], v[68:71]
	v_mfma_f32_16x16x32_bf16 v[64:67], v[176:179], v[212:215], v[64:67]
	s_setprio 0
	s_setprio 1
	v_mfma_f32_16x16x32_bf16 v[116:119], v[172:175], v[188:191], v[116:119]
	v_mfma_f32_16x16x32_bf16 v[112:115], v[180:183], v[188:191], v[112:115]
	v_mfma_f32_16x16x32_bf16 v[100:103], v[172:175], v[196:199], v[100:103]
	v_mfma_f32_16x16x32_bf16 v[96:99], v[180:183], v[196:199], v[96:99]
	s_setprio 0
	s_setprio 1
	v_mfma_f32_16x16x32_bf16 v[84:87], v[172:175], v[204:207], v[84:87]
	v_mfma_f32_16x16x32_bf16 v[80:83], v[180:183], v[204:207], v[80:83]
	v_mfma_f32_16x16x32_bf16 v[68:71], v[172:175], v[216:219], v[68:71]
	v_mfma_f32_16x16x32_bf16 v[64:67], v[180:183], v[216:219], v[64:67]
	s_setprio 0
	s_barrier
	s_add_i32 s42, s55, s10
	v_lshl_add_u64 v[144:145], v[144:145], 0, s[4:5]
	s_mov_b32 m0, s42
	ds_read_b128 v[184:187], v151 offset:49152
	ds_read_b128 v[188:191], v151 offset:50176
	ds_read_b128 v[192:195], v151 offset:51200
	ds_read_b128 v[196:199], v151 offset:52224
	ds_read_b128 v[200:203], v151 offset:53248
	ds_read_b128 v[204:207], v151 offset:54272
	ds_read_b128 v[212:215], v151 offset:55296
	ds_read_b128 v[216:219], v151 offset:56320
	global_load_lds_dwordx4 v[144:145], off
	s_add_i32 m0, s42, 0x2000
	s_add_u32 s40, s40, 0x40080
	v_lshl_add_u64 v[144:145], v[208:209], 0, s[4:5]
	s_addc_u32 s41, s41, 0
	s_add_i32 s42, s56, s10
	global_load_lds_dwordx4 v[144:145], off
	v_lshl_add_u64 v[144:145], s[40:41], 0, v[132:133]
	s_mov_b32 m0, s42
	s_nop 0
	global_load_lds_dwordx4 v[144:145], off
	v_lshl_add_u64 v[144:145], s[40:41], 0, v[128:129]
	s_add_i32 m0, s42, 0x2000
	s_nop 0
	global_load_lds_dwordx4 v[144:145], off
	v_lshl_add_u64 v[144:145], v[220:221], 0, s[4:5]
	s_mov_b32 m0, s29
	s_nop 0
	global_load_lds_dwordx4 v[144:145], off
	v_lshl_add_u64 v[144:145], v[222:223], 0, s[4:5]
	s_mov_b32 m0, s33
	s_nop 0
	global_load_lds_dwordx4 v[144:145], off
	s_waitcnt vmcnt(8)
	s_waitcnt lgkmcnt(0)
	s_barrier
	s_setprio 1
	s_waitcnt lgkmcnt(0)
	v_mfma_f32_16x16x32_bf16 v[60:63], v[152:155], v[184:187], v[60:63]
	v_mfma_f32_16x16x32_bf16 v[56:59], v[160:163], v[184:187], v[56:59]
	v_mfma_f32_16x16x32_bf16 v[44:47], v[152:155], v[192:195], v[44:47]
	v_mfma_f32_16x16x32_bf16 v[40:43], v[160:163], v[192:195], v[40:43]
	s_setprio 0
	s_setprio 1
	v_mfma_f32_16x16x32_bf16 v[28:31], v[152:155], v[200:203], v[28:31]
	v_mfma_f32_16x16x32_bf16 v[24:27], v[160:163], v[200:203], v[24:27]
	v_mfma_f32_16x16x32_bf16 v[12:15], v[152:155], v[212:215], v[12:15]
	v_mfma_f32_16x16x32_bf16 v[8:11], v[160:163], v[212:215], v[8:11]
	s_setprio 0
	s_setprio 1
	v_mfma_f32_16x16x32_bf16 v[60:63], v[156:159], v[188:191], v[60:63]
	v_mfma_f32_16x16x32_bf16 v[56:59], v[164:167], v[188:191], v[56:59]
	v_mfma_f32_16x16x32_bf16 v[44:47], v[156:159], v[196:199], v[44:47]
	v_mfma_f32_16x16x32_bf16 v[40:43], v[164:167], v[196:199], v[40:43]
	s_setprio 0
	s_setprio 1
	v_mfma_f32_16x16x32_bf16 v[28:31], v[156:159], v[204:207], v[28:31]
	v_mfma_f32_16x16x32_bf16 v[24:27], v[164:167], v[204:207], v[24:27]
	v_mfma_f32_16x16x32_bf16 v[12:15], v[156:159], v[216:219], v[12:15]
	v_mfma_f32_16x16x32_bf16 v[8:11], v[164:167], v[216:219], v[8:11]
	s_setprio 0
	s_setprio 1
	v_mfma_f32_16x16x32_bf16 v[52:55], v[168:171], v[184:187], v[52:55]
	v_mfma_f32_16x16x32_bf16 v[48:51], v[176:179], v[184:187], v[48:51]
	v_mfma_f32_16x16x32_bf16 v[36:39], v[168:171], v[192:195], v[36:39]
	v_mfma_f32_16x16x32_bf16 v[32:35], v[176:179], v[192:195], v[32:35]
	s_setprio 0
	s_setprio 1
	v_mfma_f32_16x16x32_bf16 v[20:23], v[168:171], v[200:203], v[20:23]
	v_mfma_f32_16x16x32_bf16 v[16:19], v[176:179], v[200:203], v[16:19]
	v_mfma_f32_16x16x32_bf16 v[4:7], v[168:171], v[212:215], v[4:7]
	v_mfma_f32_16x16x32_bf16 v[0:3], v[176:179], v[212:215], v[0:3]
	s_setprio 0
	s_setprio 1
	v_mfma_f32_16x16x32_bf16 v[52:55], v[172:175], v[188:191], v[52:55]
	v_mfma_f32_16x16x32_bf16 v[48:51], v[180:183], v[188:191], v[48:51]
	v_mfma_f32_16x16x32_bf16 v[36:39], v[172:175], v[196:199], v[36:39]
	v_mfma_f32_16x16x32_bf16 v[32:35], v[180:183], v[196:199], v[32:35]
	s_setprio 0
	s_setprio 1
	v_mfma_f32_16x16x32_bf16 v[20:23], v[172:175], v[204:207], v[20:23]
	v_mfma_f32_16x16x32_bf16 v[16:19], v[180:183], v[204:207], v[16:19]
	v_mfma_f32_16x16x32_bf16 v[4:7], v[172:175], v[216:219], v[4:7]
	v_mfma_f32_16x16x32_bf16 v[0:3], v[180:183], v[216:219], v[0:3]
	s_setprio 0
	s_barrier
	s_add_i32 s54, s54, 2
	s_add_u32 s38, s38, 0x100
	s_addc_u32 s39, s39, 0
	s_add_u32 s52, s52, 0x100
	s_addc_u32 s53, s53, 0
	s_cmp_gt_u32 s54, 13
	s_cbranch_scc0 .LBB0_538
	s_and_b64 vcc, exec, s[8:9]
	s_cbranch_vccz .LBB0_541
	s_barrier

.LBB0_617:
	ds_read_b128 v[32:35], v186
	ds_read_b128 v[36:39], v186 offset:1024
	ds_read_b128 v[40:43], v186 offset:2048
	ds_read_b128 v[44:47], v186 offset:3072
	ds_read_b128 v[48:51], v187
	ds_read_b128 v[52:55], v187 offset:1024
	ds_read_b128 v[56:59], v187 offset:2048
	ds_read_b128 v[60:63], v187 offset:3072
	s_add_u32 s38, s2, 0x100
	s_addc_u32 s39, s3, 0
	s_cmp_eq_u32 s52, 40
	s_cselect_b32 s43, s7, s39
	s_cselect_b32 s42, s6, s38
	s_cselect_b32 s41, s37, s51
	s_cselect_b32 s40, s36, s1
	v_lshl_add_u64 v[180:181], s[2:3], 0, v[168:169]
	s_add_i32 m0, s11, 0xc000
	ds_read_b128 v[176:179], v188
	ds_read_b128 v[190:193], v188 offset:1024
	ds_read_b128 v[194:197], v188 offset:2048
	ds_read_b128 v[198:201], v188 offset:3072
	ds_read_b128 v[202:205], v188 offset:4096
	ds_read_b128 v[206:209], v188 offset:5120
	ds_read_b128 v[212:215], v188 offset:6144
	ds_read_b128 v[216:219], v188 offset:7168
	global_load_lds_dwordx4 v[180:181], off
	v_lshl_add_u64 v[180:181], s[2:3], 0, v[170:171]
	s_add_i32 m0, s11, 0xe000
	s_nop 0
	global_load_lds_dwordx4 v[180:181], off
	s_waitcnt vmcnt(8)
	s_waitcnt lgkmcnt(0)
	s_barrier
	s_setprio 1
	s_waitcnt lgkmcnt(0)
	v_mfma_f32_16x16x32_bf16 v[156:159], v[32:35], v[176:179], v[156:159]
	v_mfma_f32_16x16x32_bf16 v[152:155], v[40:43], v[176:179], v[152:155]
	v_mfma_f32_16x16x32_bf16 v[140:143], v[32:35], v[194:197], v[140:143]
	v_mfma_f32_16x16x32_bf16 v[136:139], v[40:43], v[194:197], v[136:139]
	s_setprio 0
	s_setprio 1
	v_mfma_f32_16x16x32_bf16 v[124:127], v[32:35], v[202:205], v[124:127]
	v_mfma_f32_16x16x32_bf16 v[120:123], v[40:43], v[202:205], v[120:123]
	v_mfma_f32_16x16x32_bf16 v[108:111], v[32:35], v[212:215], v[108:111]
	v_mfma_f32_16x16x32_bf16 v[104:107], v[40:43], v[212:215], v[104:107]
	s_setprio 0
	s_setprio 1
	v_mfma_f32_16x16x32_bf16 v[156:159], v[36:39], v[190:193], v[156:159]
	v_mfma_f32_16x16x32_bf16 v[152:155], v[44:47], v[190:193], v[152:155]
	v_mfma_f32_16x16x32_bf16 v[140:143], v[36:39], v[198:201], v[140:143]
	v_mfma_f32_16x16x32_bf16 v[136:139], v[44:47], v[198:201], v[136:139]
	s_setprio 0
	s_setprio 1
	v_mfma_f32_16x16x32_bf16 v[124:127], v[36:39], v[206:209], v[124:127]
	v_mfma_f32_16x16x32_bf16 v[120:123], v[44:47], v[206:209], v[120:123]
	v_mfma_f32_16x16x32_bf16 v[108:111], v[36:39], v[216:219], v[108:111]
	v_mfma_f32_16x16x32_bf16 v[104:107], v[44:47], v[216:219], v[104:107]
	s_setprio 0
	s_setprio 1
	v_mfma_f32_16x16x32_bf16 v[148:151], v[48:51], v[176:179], v[148:151]
	v_mfma_f32_16x16x32_bf16 v[144:147], v[56:59], v[176:179], v[144:147]
	v_mfma_f32_16x16x32_bf16 v[132:135], v[48:51], v[194:197], v[132:135]
	v_mfma_f32_16x16x32_bf16 v[128:131], v[56:59], v[194:197], v[128:131]
	s_setprio 0
	s_setprio 1
	v_mfma_f32_16x16x32_bf16 v[116:119], v[48:51], v[202:205], v[116:119]
	v_mfma_f32_16x16x32_bf16 v[112:115], v[56:59], v[202:205], v[112:115]
	v_mfma_f32_16x16x32_bf16 v[100:103], v[48:51], v[212:215], v[100:103]
	v_mfma_f32_16x16x32_bf16 v[96:99], v[56:59], v[212:215], v[96:99]
	s_setprio 0
	s_setprio 1
	v_mfma_f32_16x16x32_bf16 v[148:151], v[52:55], v[190:193], v[148:151]
	v_mfma_f32_16x16x32_bf16 v[144:147], v[60:63], v[190:193], v[144:147]
	v_mfma_f32_16x16x32_bf16 v[132:135], v[52:55], v[198:201], v[132:135]
	v_mfma_f32_16x16x32_bf16 v[128:131], v[60:63], v[198:201], v[128:131]
	s_setprio 0
	s_setprio 1
	v_mfma_f32_16x16x32_bf16 v[116:119], v[52:55], v[206:209], v[116:119]
	v_mfma_f32_16x16x32_bf16 v[112:115], v[60:63], v[206:209], v[112:115]
	v_mfma_f32_16x16x32_bf16 v[100:103], v[52:55], v[216:219], v[100:103]
	v_mfma_f32_16x16x32_bf16 v[96:99], v[60:63], v[216:219], v[96:99]
	s_setprio 0
	s_barrier
	s_add_i32 s2, s46, s10
	v_lshl_add_u64 v[180:181], s[40:41], 0, v[162:163]
	s_mov_b32 m0, s2
	ds_read_b128 v[176:179], v188 offset:16384
	ds_read_b128 v[190:193], v188 offset:17408
	ds_read_b128 v[194:197], v188 offset:18432
	ds_read_b128 v[198:201], v188 offset:19456
	ds_read_b128 v[202:205], v188 offset:20480
	ds_read_b128 v[206:209], v188 offset:21504
	ds_read_b128 v[212:215], v188 offset:22528
	ds_read_b128 v[216:219], v188 offset:23552
	global_load_lds_dwordx4 v[180:181], off
	s_add_i32 m0, s2, 0x2000
	s_add_u32 s2, s40, 0xb0000
	v_lshl_add_u64 v[228:229], s[40:41], 0, v[166:167]
	s_addc_u32 s3, s41, 0
	s_add_i32 s53, s47, s10
	global_load_lds_dwordx4 v[228:229], off
	v_lshl_add_u64 v[220:221], s[2:3], 0, v[162:163]
	s_mov_b32 m0, s53
	v_lshl_add_u64 v[230:231], s[42:43], 0, v[160:161]
	global_load_lds_dwordx4 v[220:221], off
	v_lshl_add_u64 v[220:221], s[2:3], 0, v[166:167]
	s_add_i32 m0, s53, 0x2000
	v_lshl_add_u64 v[232:233], s[42:43], 0, v[164:165]
	global_load_lds_dwordx4 v[220:221], off
	s_mov_b32 m0, s11
	s_nop 0
	global_load_lds_dwordx4 v[230:231], off
	s_mov_b32 m0, s14
	s_nop 0
	global_load_lds_dwordx4 v[232:233], off
	s_waitcnt vmcnt(8)
	s_waitcnt lgkmcnt(0)
	s_barrier
	s_setprio 1
	s_waitcnt lgkmcnt(0)
	v_mfma_f32_16x16x32_bf16 v[92:95], v[32:35], v[176:179], v[92:95]
	v_mfma_f32_16x16x32_bf16 v[88:91], v[40:43], v[176:179], v[88:91]
	v_mfma_f32_16x16x32_bf16 v[76:79], v[32:35], v[194:197], v[76:79]
	v_mfma_f32_16x16x32_bf16 v[72:75], v[40:43], v[194:197], v[72:75]
	s_setprio 0
	s_setprio 1
	v_mfma_f32_16x16x32_bf16 v[28:31], v[32:35], v[202:205], v[28:31]
	v_mfma_f32_16x16x32_bf16 v[24:27], v[40:43], v[202:205], v[24:27]
	v_mfma_f32_16x16x32_bf16 v[12:15], v[32:35], v[212:215], v[12:15]
	v_mfma_f32_16x16x32_bf16 v[8:11], v[40:43], v[212:215], v[8:11]
	s_setprio 0
	s_setprio 1
	v_mfma_f32_16x16x32_bf16 v[92:95], v[36:39], v[190:193], v[92:95]
	v_mfma_f32_16x16x32_bf16 v[88:91], v[44:47], v[190:193], v[88:91]
	v_mfma_f32_16x16x32_bf16 v[76:79], v[36:39], v[198:201], v[76:79]
	v_mfma_f32_16x16x32_bf16 v[72:75], v[44:47], v[198:201], v[72:75]
	s_setprio 0
	s_setprio 1
	v_mfma_f32_16x16x32_bf16 v[28:31], v[36:39], v[206:209], v[28:31]
	v_mfma_f32_16x16x32_bf16 v[24:27], v[44:47], v[206:209], v[24:27]
	v_mfma_f32_16x16x32_bf16 v[12:15], v[36:39], v[216:219], v[12:15]
	v_mfma_f32_16x16x32_bf16 v[8:11], v[44:47], v[216:219], v[8:11]
	s_setprio 0
	s_setprio 1
	v_mfma_f32_16x16x32_bf16 v[20:23], v[48:51], v[202:205], v[20:23]
	v_mfma_f32_16x16x32_bf16 v[16:19], v[56:59], v[202:205], v[16:19]
	v_mfma_f32_16x16x32_bf16 v[4:7], v[48:51], v[212:215], v[4:7]
	v_mfma_f32_16x16x32_bf16 v[0:3], v[56:59], v[212:215], v[0:3]
	s_setprio 0
	s_setprio 1
	v_mfma_f32_16x16x32_bf16 v[32:35], v[48:51], v[176:179], v[84:87]
	v_mfma_f32_16x16x32_bf16 v[36:39], v[56:59], v[176:179], v[80:83]
	v_mfma_f32_16x16x32_bf16 v[40:43], v[48:51], v[194:197], v[68:71]
	v_mfma_f32_16x16x32_bf16 v[44:47], v[56:59], v[194:197], v[64:67]
	s_setprio 0
	s_setprio 1
	v_mfma_f32_16x16x32_bf16 v[20:23], v[52:55], v[206:209], v[20:23]
	v_mfma_f32_16x16x32_bf16 v[16:19], v[60:63], v[206:209], v[16:19]
	v_mfma_f32_16x16x32_bf16 v[4:7], v[52:55], v[216:219], v[4:7]
	v_mfma_f32_16x16x32_bf16 v[0:3], v[60:63], v[216:219], v[0:3]
	s_setprio 0
	s_setprio 1
	v_mfma_f32_16x16x32_bf16 v[32:35], v[52:55], v[190:193], v[32:35]
	v_mfma_f32_16x16x32_bf16 v[36:39], v[60:63], v[190:193], v[36:39]
	v_mfma_f32_16x16x32_bf16 v[40:43], v[52:55], v[198:201], v[40:43]
	v_mfma_f32_16x16x32_bf16 v[44:47], v[60:63], v[198:201], v[44:47]
	s_setprio 0
	s_barrier
	s_add_i32 s53, 0, 0x18000
	s_add_i32 s54, 0, 0x1c000
	v_add_u32_e32 v60, s53, v183
	v_add_u32_e32 v64, s54, v183
	ds_read_b128 v[48:51], v60
	ds_read_b128 v[52:55], v60 offset:1024
	ds_read_b128 v[56:59], v60 offset:2048
	ds_read_b128 v[60:63], v60 offset:3072
	ds_read_b128 v[176:179], v64
	ds_read_b128 v[190:193], v64 offset:1024
	ds_read_b128 v[194:197], v64 offset:2048
	ds_read_b128 v[198:201], v64 offset:3072
	s_add_u32 s2, s42, 0xb0000
	s_addc_u32 s3, s43, 0
	s_mov_b32 m0, s15
	v_lshl_add_u64 v[220:221], s[2:3], 0, v[160:161]
	ds_read_b128 v[64:67], v188 offset:32768
	ds_read_b128 v[68:71], v188 offset:33792
	ds_read_b128 v[80:83], v188 offset:34816
	ds_read_b128 v[84:87], v188 offset:35840
	ds_read_b128 v[202:205], v188 offset:36864
	ds_read_b128 v[206:209], v188 offset:37888
	ds_read_b128 v[212:215], v188 offset:38912
	ds_read_b128 v[216:219], v188 offset:39936
	global_load_lds_dwordx4 v[220:221], off
	v_lshl_add_u64 v[220:221], s[2:3], 0, v[164:165]
	s_mov_b32 m0, s28
	s_nop 0
	global_load_lds_dwordx4 v[220:221], off
	s_waitcnt vmcnt(8)
	s_waitcnt lgkmcnt(0)
	s_barrier
	s_setprio 1
	s_waitcnt lgkmcnt(0)
	v_mfma_f32_16x16x32_bf16 v[156:159], v[48:51], v[64:67], v[156:159]
	v_mfma_f32_16x16x32_bf16 v[152:155], v[56:59], v[64:67], v[152:155]
	v_mfma_f32_16x16x32_bf16 v[140:143], v[48:51], v[80:83], v[140:143]
	v_mfma_f32_16x16x32_bf16 v[136:139], v[56:59], v[80:83], v[136:139]
	s_setprio 0
	s_setprio 1
	v_mfma_f32_16x16x32_bf16 v[124:127], v[48:51], v[202:205], v[124:127]
	v_mfma_f32_16x16x32_bf16 v[120:123], v[56:59], v[202:205], v[120:123]
	v_mfma_f32_16x16x32_bf16 v[108:111], v[48:51], v[212:215], v[108:111]
	v_mfma_f32_16x16x32_bf16 v[104:107], v[56:59], v[212:215], v[104:107]
	s_setprio 0
	s_setprio 1
	v_mfma_f32_16x16x32_bf16 v[156:159], v[52:55], v[68:71], v[156:159]
	v_mfma_f32_16x16x32_bf16 v[152:155], v[60:63], v[68:71], v[152:155]
	v_mfma_f32_16x16x32_bf16 v[140:143], v[52:55], v[84:87], v[140:143]
	v_mfma_f32_16x16x32_bf16 v[136:139], v[60:63], v[84:87], v[136:139]
	s_setprio 0
	s_setprio 1
	v_mfma_f32_16x16x32_bf16 v[124:127], v[52:55], v[206:209], v[124:127]
	v_mfma_f32_16x16x32_bf16 v[120:123], v[60:63], v[206:209], v[120:123]
	v_mfma_f32_16x16x32_bf16 v[108:111], v[52:55], v[216:219], v[108:111]
	v_mfma_f32_16x16x32_bf16 v[104:107], v[60:63], v[216:219], v[104:107]
	s_setprio 0
	s_setprio 1
	v_mfma_f32_16x16x32_bf16 v[148:151], v[176:179], v[64:67], v[148:151]
	v_mfma_f32_16x16x32_bf16 v[64:67], v[194:197], v[64:67], v[144:147]
	v_mfma_f32_16x16x32_bf16 v[144:147], v[198:201], v[68:71], v[64:67]
	v_mfma_f32_16x16x32_bf16 v[64:67], v[176:179], v[80:83], v[132:135]
	s_setprio 0
	s_setprio 1
	v_mfma_f32_16x16x32_bf16 v[132:135], v[190:193], v[84:87], v[64:67]
	v_mfma_f32_16x16x32_bf16 v[64:67], v[194:197], v[80:83], v[128:131]
	v_mfma_f32_16x16x32_bf16 v[128:131], v[198:201], v[84:87], v[64:67]
	v_mfma_f32_16x16x32_bf16 v[64:67], v[176:179], v[202:205], v[116:119]
	s_setprio 0
	s_setprio 1
	v_mfma_f32_16x16x32_bf16 v[116:119], v[190:193], v[206:209], v[64:67]
	v_mfma_f32_16x16x32_bf16 v[64:67], v[194:197], v[202:205], v[112:115]
	v_mfma_f32_16x16x32_bf16 v[112:115], v[198:201], v[206:209], v[64:67]
	v_mfma_f32_16x16x32_bf16 v[64:67], v[176:179], v[212:215], v[100:103]
	s_setprio 0
	s_setprio 1
	v_mfma_f32_16x16x32_bf16 v[100:103], v[190:193], v[216:219], v[64:67]
	v_mfma_f32_16x16x32_bf16 v[64:67], v[194:197], v[212:215], v[96:99]
	v_mfma_f32_16x16x32_bf16 v[148:151], v[190:193], v[68:71], v[148:151]
	v_mfma_f32_16x16x32_bf16 v[96:99], v[198:201], v[216:219], v[64:67]
	s_setprio 0
	s_barrier
	s_add_i32 s2, s53, s10
	v_lshl_add_u64 v[80:81], v[180:181], 0, s[26:27]
	s_mov_b32 m0, s2
	s_nop 0
	ds_read_b128 v[64:67], v188 offset:49152
	ds_read_b128 v[68:71], v188 offset:50176
	ds_read_b128 v[202:205], v188 offset:51200
	ds_read_b128 v[206:209], v188 offset:52224
	ds_read_b128 v[212:215], v188 offset:53248
	ds_read_b128 v[216:219], v188 offset:54272
	ds_read_b128 v[220:223], v188 offset:55296
	ds_read_b128 v[224:227], v188 offset:56320
	global_load_lds_dwordx4 v[80:81], off
	s_add_i32 m0, s2, 0x2000
	s_add_u32 s2, s40, 0xb0080
	v_lshl_add_u64 v[80:81], v[228:229], 0, s[26:27]
	s_addc_u32 s3, s41, 0
	s_add_i32 s40, s54, s10
	global_load_lds_dwordx4 v[80:81], off
	v_lshl_add_u64 v[80:81], s[2:3], 0, v[162:163]
	s_mov_b32 m0, s40
	s_nop 0
	global_load_lds_dwordx4 v[80:81], off
	v_lshl_add_u64 v[80:81], s[2:3], 0, v[166:167]
	s_add_i32 m0, s40, 0x2000
	s_nop 0
	global_load_lds_dwordx4 v[80:81], off
	v_lshl_add_u64 v[80:81], v[230:231], 0, s[26:27]
	s_mov_b32 m0, s33
	s_nop 0
	global_load_lds_dwordx4 v[80:81], off
	v_lshl_add_u64 v[80:81], v[232:233], 0, s[26:27]
	s_mov_b32 m0, s44
	s_nop 0
	global_load_lds_dwordx4 v[80:81], off
	s_waitcnt vmcnt(8)
	s_waitcnt lgkmcnt(0)
	s_barrier
	s_setprio 1
	s_waitcnt lgkmcnt(0)
	v_mfma_f32_16x16x32_bf16 v[80:83], v[48:51], v[64:67], v[92:95]
	v_mfma_f32_16x16x32_bf16 v[92:95], v[52:55], v[68:71], v[80:83]
	v_mfma_f32_16x16x32_bf16 v[80:83], v[56:59], v[64:67], v[88:91]
	v_mfma_f32_16x16x32_bf16 v[76:79], v[48:51], v[202:205], v[76:79]
	s_setprio 0
	s_setprio 1
	v_mfma_f32_16x16x32_bf16 v[72:75], v[56:59], v[202:205], v[72:75]
	v_mfma_f32_16x16x32_bf16 v[28:31], v[48:51], v[212:215], v[28:31]
	v_mfma_f32_16x16x32_bf16 v[24:27], v[56:59], v[212:215], v[24:27]
	v_mfma_f32_16x16x32_bf16 v[12:15], v[48:51], v[220:223], v[12:15]
	s_setprio 0
	s_setprio 1
	v_mfma_f32_16x16x32_bf16 v[8:11], v[56:59], v[220:223], v[8:11]
	v_mfma_f32_16x16x32_bf16 v[88:91], v[60:63], v[68:71], v[80:83]
	v_mfma_f32_16x16x32_bf16 v[76:79], v[52:55], v[206:209], v[76:79]
	v_mfma_f32_16x16x32_bf16 v[72:75], v[60:63], v[206:209], v[72:75]
	s_setprio 0
	s_setprio 1
	v_mfma_f32_16x16x32_bf16 v[28:31], v[52:55], v[216:219], v[28:31]
	v_mfma_f32_16x16x32_bf16 v[24:27], v[60:63], v[216:219], v[24:27]
	v_mfma_f32_16x16x32_bf16 v[12:15], v[52:55], v[224:227], v[12:15]
	v_mfma_f32_16x16x32_bf16 v[8:11], v[60:63], v[224:227], v[8:11]
	s_setprio 0
	s_setprio 1
	v_mfma_f32_16x16x32_bf16 v[32:35], v[176:179], v[64:67], v[32:35]
	v_mfma_f32_16x16x32_bf16 v[84:87], v[190:193], v[68:71], v[32:35]
	v_mfma_f32_16x16x32_bf16 v[32:35], v[194:197], v[64:67], v[36:39]
	v_mfma_f32_16x16x32_bf16 v[80:83], v[198:201], v[68:71], v[32:35]
	s_setprio 0
	s_setprio 1
	v_mfma_f32_16x16x32_bf16 v[32:35], v[176:179], v[202:205], v[40:43]
	v_mfma_f32_16x16x32_bf16 v[68:71], v[190:193], v[206:209], v[32:35]
	v_mfma_f32_16x16x32_bf16 v[32:35], v[194:197], v[202:205], v[44:47]
	v_mfma_f32_16x16x32_bf16 v[20:23], v[176:179], v[212:215], v[20:23]
	s_setprio 0
	s_setprio 1
	v_mfma_f32_16x16x32_bf16 v[16:19], v[194:197], v[212:215], v[16:19]
	v_mfma_f32_16x16x32_bf16 v[4:7], v[176:179], v[220:223], v[4:7]
	v_mfma_f32_16x16x32_bf16 v[0:3], v[194:197], v[220:223], v[0:3]
	v_mfma_f32_16x16x32_bf16 v[64:67], v[198:201], v[206:209], v[32:35]
	s_setprio 0
	s_setprio 1
	v_mfma_f32_16x16x32_bf16 v[20:23], v[190:193], v[216:219], v[20:23]
	v_mfma_f32_16x16x32_bf16 v[16:19], v[198:201], v[216:219], v[16:19]
	v_mfma_f32_16x16x32_bf16 v[4:7], v[190:193], v[224:227], v[4:7]
	v_mfma_f32_16x16x32_bf16 v[0:3], v[198:201], v[224:227], v[0:3]
	s_setprio 0
	s_barrier
	s_add_i32 s52, s52, 2
	s_add_u32 s1, s1, 0x100
	s_addc_u32 s51, s51, 0
	s_cmp_gt_u32 s52, 41
	s_mov_b64 s[2:3], s[38:39]
	s_cbranch_scc0 .LBB0_617
	s_and_b64 vcc, exec, s[34:35]
	s_cbranch_vccz .LBB0_620
	s_barrier

.LBB0_704:
	ds_read_b128 v[128:131], v214
	ds_read_b128 v[132:135], v214 offset:1024
	ds_read_b128 v[136:139], v214 offset:2048
	ds_read_b128 v[140:143], v214 offset:3072
	ds_read_b128 v[144:147], v215
	ds_read_b128 v[148:151], v215 offset:1024
	ds_read_b128 v[168:171], v215 offset:2048
	ds_read_b128 v[172:175], v215 offset:3072
	s_add_u32 s6, s4, 0xfffc0080
	s_addc_u32 s7, s5, -1
	s_cmp_eq_u32 s57, 12
	s_cselect_b32 s63, s3, s7
	s_cselect_b32 s62, s11, s6
	s_cselect_b32 s7, s14, s55
	s_cselect_b32 s6, s15, s28
	v_lshl_add_u64 v[208:209], s[4:5], 0, v[160:161]
	s_add_i32 m0, s64, 0xc000
	ds_read_b128 v[176:179], v216
	ds_read_b128 v[180:183], v216 offset:1024
	ds_read_b128 v[184:187], v216 offset:2048
	ds_read_b128 v[188:191], v216 offset:3072
	ds_read_b128 v[192:195], v216 offset:4096
	ds_read_b128 v[196:199], v216 offset:5120
	ds_read_b128 v[200:203], v216 offset:6144
	ds_read_b128 v[204:207], v216 offset:7168
	global_load_lds_dwordx4 v[208:209], off
	v_lshl_add_u64 v[208:209], s[4:5], 0, v[162:163]
	s_add_i32 m0, s64, 0xe000
	s_nop 0
	global_load_lds_dwordx4 v[208:209], off
	s_waitcnt vmcnt(8)
	s_waitcnt lgkmcnt(0)
	s_barrier
	s_setprio 1
	s_waitcnt lgkmcnt(0)
	v_mfma_f32_16x16x32_bf16 v[124:127], v[128:131], v[176:179], v[124:127]
	v_mfma_f32_16x16x32_bf16 v[120:123], v[136:139], v[176:179], v[120:123]
	v_mfma_f32_16x16x32_bf16 v[116:119], v[128:131], v[184:187], v[116:119]
	v_mfma_f32_16x16x32_bf16 v[112:115], v[136:139], v[184:187], v[112:115]
	s_setprio 0
	s_setprio 1
	v_mfma_f32_16x16x32_bf16 v[108:111], v[128:131], v[192:195], v[108:111]
	v_mfma_f32_16x16x32_bf16 v[100:103], v[136:139], v[192:195], v[100:103]
	v_mfma_f32_16x16x32_bf16 v[88:91], v[128:131], v[200:203], v[88:91]
	v_mfma_f32_16x16x32_bf16 v[80:83], v[136:139], v[200:203], v[80:83]
	s_setprio 0
	s_setprio 1
	v_mfma_f32_16x16x32_bf16 v[124:127], v[132:135], v[180:183], v[124:127]
	v_mfma_f32_16x16x32_bf16 v[120:123], v[140:143], v[180:183], v[120:123]
	v_mfma_f32_16x16x32_bf16 v[116:119], v[132:135], v[188:191], v[116:119]
	v_mfma_f32_16x16x32_bf16 v[112:115], v[140:143], v[188:191], v[112:115]
	s_setprio 0
	s_setprio 1
	v_mfma_f32_16x16x32_bf16 v[108:111], v[132:135], v[196:199], v[108:111]
	v_mfma_f32_16x16x32_bf16 v[100:103], v[140:143], v[196:199], v[100:103]
	v_mfma_f32_16x16x32_bf16 v[88:91], v[132:135], v[204:207], v[88:91]
	v_mfma_f32_16x16x32_bf16 v[80:83], v[140:143], v[204:207], v[80:83]
	s_setprio 0
	s_setprio 1
	v_mfma_f32_16x16x32_bf16 v[104:107], v[144:147], v[176:179], v[104:107]
	v_mfma_f32_16x16x32_bf16 v[96:99], v[168:171], v[176:179], v[96:99]
	v_mfma_f32_16x16x32_bf16 v[92:95], v[144:147], v[184:187], v[92:95]
	v_mfma_f32_16x16x32_bf16 v[84:87], v[168:171], v[184:187], v[84:87]
	s_setprio 0
	s_setprio 1
	v_mfma_f32_16x16x32_bf16 v[76:79], v[144:147], v[192:195], v[76:79]
	v_mfma_f32_16x16x32_bf16 v[72:75], v[168:171], v[192:195], v[72:75]
	v_mfma_f32_16x16x32_bf16 v[68:71], v[144:147], v[200:203], v[68:71]
	v_mfma_f32_16x16x32_bf16 v[64:67], v[168:171], v[200:203], v[64:67]
	s_setprio 0
	s_setprio 1
	v_mfma_f32_16x16x32_bf16 v[104:107], v[148:151], v[180:183], v[104:107]
	v_mfma_f32_16x16x32_bf16 v[96:99], v[172:175], v[180:183], v[96:99]
	v_mfma_f32_16x16x32_bf16 v[92:95], v[148:151], v[188:191], v[92:95]
	v_mfma_f32_16x16x32_bf16 v[84:87], v[172:175], v[188:191], v[84:87]
	s_setprio 0
	s_setprio 1
	v_mfma_f32_16x16x32_bf16 v[76:79], v[148:151], v[196:199], v[76:79]
	v_mfma_f32_16x16x32_bf16 v[72:75], v[172:175], v[196:199], v[72:75]
	v_mfma_f32_16x16x32_bf16 v[68:71], v[148:151], v[204:207], v[68:71]
	v_mfma_f32_16x16x32_bf16 v[64:67], v[172:175], v[204:207], v[64:67]
	s_setprio 0
	s_barrier
	s_add_i32 s68, s79, s33
	v_lshl_add_u64 v[208:209], s[6:7], 0, v[156:157]
	s_mov_b32 m0, s68
	ds_read_b128 v[176:179], v216 offset:16384
	ds_read_b128 v[180:183], v216 offset:17408
	ds_read_b128 v[184:187], v216 offset:18432
	ds_read_b128 v[188:191], v216 offset:19456
	ds_read_b128 v[192:195], v216 offset:20480
	ds_read_b128 v[196:199], v216 offset:21504
	ds_read_b128 v[200:203], v216 offset:22528
	ds_read_b128 v[204:207], v216 offset:23552
	global_load_lds_dwordx4 v[208:209], off
	s_add_i32 m0, s68, 0x2000
	s_add_u32 s84, s6, 0x40000
	v_lshl_add_u64 v[220:221], s[6:7], 0, v[152:153]
	s_addc_u32 s85, s7, 0
	s_add_i32 s68, s80, s33
	global_load_lds_dwordx4 v[220:221], off
	v_lshl_add_u64 v[222:223], s[84:85], 0, v[156:157]
	s_mov_b32 m0, s68
	v_lshl_add_u64 v[224:225], s[62:63], 0, v[154:155]
	global_load_lds_dwordx4 v[222:223], off
	v_lshl_add_u64 v[222:223], s[84:85], 0, v[152:153]
	s_add_i32 m0, s68, 0x2000
	s_nop 0
	global_load_lds_dwordx4 v[222:223], off
	v_lshl_add_u64 v[222:223], s[62:63], 0, v[158:159]
	s_mov_b32 m0, s64
	s_nop 0
	global_load_lds_dwordx4 v[222:223], off
	s_mov_b32 m0, s65
	s_nop 0
	global_load_lds_dwordx4 v[224:225], off
	s_waitcnt vmcnt(8)
	s_waitcnt lgkmcnt(0)
	s_barrier
	s_setprio 1
	s_waitcnt lgkmcnt(0)
	v_mfma_f32_16x16x32_bf16 v[60:63], v[128:131], v[176:179], v[60:63]
	v_mfma_f32_16x16x32_bf16 v[56:59], v[136:139], v[176:179], v[56:59]
	v_mfma_f32_16x16x32_bf16 v[52:55], v[128:131], v[184:187], v[52:55]
	v_mfma_f32_16x16x32_bf16 v[48:51], v[136:139], v[184:187], v[48:51]
	s_setprio 0
	s_setprio 1
	v_mfma_f32_16x16x32_bf16 v[40:43], v[128:131], v[192:195], v[40:43]
	v_mfma_f32_16x16x32_bf16 v[32:35], v[136:139], v[192:195], v[32:35]
	v_mfma_f32_16x16x32_bf16 v[20:23], v[128:131], v[200:203], v[20:23]
	v_mfma_f32_16x16x32_bf16 v[16:19], v[136:139], v[200:203], v[16:19]
	s_setprio 0
	s_setprio 1
	v_mfma_f32_16x16x32_bf16 v[60:63], v[132:135], v[180:183], v[60:63]
	v_mfma_f32_16x16x32_bf16 v[56:59], v[140:143], v[180:183], v[56:59]
	v_mfma_f32_16x16x32_bf16 v[52:55], v[132:135], v[188:191], v[52:55]
	v_mfma_f32_16x16x32_bf16 v[48:51], v[140:143], v[188:191], v[48:51]
	s_setprio 0
	s_setprio 1
	v_mfma_f32_16x16x32_bf16 v[40:43], v[132:135], v[196:199], v[40:43]
	v_mfma_f32_16x16x32_bf16 v[32:35], v[140:143], v[196:199], v[32:35]
	v_mfma_f32_16x16x32_bf16 v[20:23], v[132:135], v[204:207], v[20:23]
	v_mfma_f32_16x16x32_bf16 v[16:19], v[140:143], v[204:207], v[16:19]
	s_setprio 0
	s_setprio 1
	v_mfma_f32_16x16x32_bf16 v[44:47], v[144:147], v[176:179], v[44:47]
	v_mfma_f32_16x16x32_bf16 v[36:39], v[168:171], v[176:179], v[36:39]
	v_mfma_f32_16x16x32_bf16 v[28:31], v[144:147], v[184:187], v[28:31]
	v_mfma_f32_16x16x32_bf16 v[24:27], v[168:171], v[184:187], v[24:27]
	s_setprio 0
	s_setprio 1
	v_mfma_f32_16x16x32_bf16 v[12:15], v[144:147], v[192:195], v[12:15]
	v_mfma_f32_16x16x32_bf16 v[8:11], v[168:171], v[192:195], v[8:11]
	v_mfma_f32_16x16x32_bf16 v[4:7], v[144:147], v[200:203], v[4:7]
	v_mfma_f32_16x16x32_bf16 v[0:3], v[168:171], v[200:203], v[0:3]
	s_setprio 0
	s_setprio 1
	v_mfma_f32_16x16x32_bf16 v[44:47], v[148:151], v[180:183], v[44:47]
	v_mfma_f32_16x16x32_bf16 v[36:39], v[172:175], v[180:183], v[36:39]
	v_mfma_f32_16x16x32_bf16 v[28:31], v[148:151], v[188:191], v[28:31]
	v_mfma_f32_16x16x32_bf16 v[24:27], v[172:175], v[188:191], v[24:27]
	s_setprio 0
	s_setprio 1
	v_mfma_f32_16x16x32_bf16 v[12:15], v[148:151], v[196:199], v[12:15]
	v_mfma_f32_16x16x32_bf16 v[8:11], v[172:175], v[196:199], v[8:11]
	v_mfma_f32_16x16x32_bf16 v[4:7], v[148:151], v[204:207], v[4:7]
	v_mfma_f32_16x16x32_bf16 v[0:3], v[172:175], v[204:207], v[0:3]
	s_setprio 0
	s_barrier
	s_add_i32 s68, 0, 0x18000
	s_add_i32 s83, 0, 0x1c000
	v_add_u32_e32 v140, s68, v213
	v_add_u32_e32 v172, s83, v213
	ds_read_b128 v[128:131], v140
	ds_read_b128 v[132:135], v140 offset:1024
	ds_read_b128 v[136:139], v140 offset:2048
	ds_read_b128 v[140:143], v140 offset:3072
	ds_read_b128 v[144:147], v172
	ds_read_b128 v[148:151], v172 offset:1024
	ds_read_b128 v[168:171], v172 offset:2048
	ds_read_b128 v[172:175], v172 offset:3072
	s_add_u32 s62, s62, 0x40000
	s_addc_u32 s63, s63, 0
	s_mov_b32 m0, s66
	v_lshl_add_u64 v[226:227], s[62:63], 0, v[158:159]
	ds_read_b128 v[176:179], v216 offset:32768
	ds_read_b128 v[180:183], v216 offset:33792
	ds_read_b128 v[184:187], v216 offset:34816
	ds_read_b128 v[188:191], v216 offset:35840
	ds_read_b128 v[192:195], v216 offset:36864
	ds_read_b128 v[196:199], v216 offset:37888
	ds_read_b128 v[200:203], v216 offset:38912
	ds_read_b128 v[204:207], v216 offset:39936
	global_load_lds_dwordx4 v[226:227], off
	v_lshl_add_u64 v[226:227], s[62:63], 0, v[154:155]
	s_mov_b32 m0, s67
	s_nop 0
	global_load_lds_dwordx4 v[226:227], off
	s_waitcnt vmcnt(8)
	s_waitcnt lgkmcnt(0)
	s_barrier
	s_setprio 1
	s_waitcnt lgkmcnt(0)
	v_mfma_f32_16x16x32_bf16 v[124:127], v[128:131], v[176:179], v[124:127]
	v_mfma_f32_16x16x32_bf16 v[120:123], v[136:139], v[176:179], v[120:123]
	v_mfma_f32_16x16x32_bf16 v[116:119], v[128:131], v[184:187], v[116:119]
	v_mfma_f32_16x16x32_bf16 v[112:115], v[136:139], v[184:187], v[112:115]
	s_setprio 0
	s_setprio 1
	v_mfma_f32_16x16x32_bf16 v[108:111], v[128:131], v[192:195], v[108:111]
	v_mfma_f32_16x16x32_bf16 v[100:103], v[136:139], v[192:195], v[100:103]
	v_mfma_f32_16x16x32_bf16 v[88:91], v[128:131], v[200:203], v[88:91]
	v_mfma_f32_16x16x32_bf16 v[80:83], v[136:139], v[200:203], v[80:83]
	s_setprio 0
	s_setprio 1
	v_mfma_f32_16x16x32_bf16 v[124:127], v[132:135], v[180:183], v[124:127]
	v_mfma_f32_16x16x32_bf16 v[120:123], v[140:143], v[180:183], v[120:123]
	v_mfma_f32_16x16x32_bf16 v[116:119], v[132:135], v[188:191], v[116:119]
	v_mfma_f32_16x16x32_bf16 v[112:115], v[140:143], v[188:191], v[112:115]
	s_setprio 0
	s_setprio 1
	v_mfma_f32_16x16x32_bf16 v[108:111], v[132:135], v[196:199], v[108:111]
	v_mfma_f32_16x16x32_bf16 v[100:103], v[140:143], v[196:199], v[100:103]
	v_mfma_f32_16x16x32_bf16 v[88:91], v[132:135], v[204:207], v[88:91]
	v_mfma_f32_16x16x32_bf16 v[80:83], v[140:143], v[204:207], v[80:83]
	s_setprio 0
	s_setprio 1
	v_mfma_f32_16x16x32_bf16 v[104:107], v[144:147], v[176:179], v[104:107]
	v_mfma_f32_16x16x32_bf16 v[96:99], v[168:171], v[176:179], v[96:99]
	v_mfma_f32_16x16x32_bf16 v[92:95], v[144:147], v[184:187], v[92:95]
	v_mfma_f32_16x16x32_bf16 v[84:87], v[168:171], v[184:187], v[84:87]
	s_setprio 0
	s_setprio 1
	v_mfma_f32_16x16x32_bf16 v[76:79], v[144:147], v[192:195], v[76:79]
	v_mfma_f32_16x16x32_bf16 v[72:75], v[168:171], v[192:195], v[72:75]
	v_mfma_f32_16x16x32_bf16 v[68:71], v[144:147], v[200:203], v[68:71]
	v_mfma_f32_16x16x32_bf16 v[64:67], v[168:171], v[200:203], v[64:67]
	s_setprio 0
	s_setprio 1
	v_mfma_f32_16x16x32_bf16 v[104:107], v[148:151], v[180:183], v[104:107]
	v_mfma_f32_16x16x32_bf16 v[96:99], v[172:175], v[180:183], v[96:99]
	v_mfma_f32_16x16x32_bf16 v[92:95], v[148:151], v[188:191], v[92:95]
	v_mfma_f32_16x16x32_bf16 v[84:87], v[172:175], v[188:191], v[84:87]
	s_setprio 0
	s_setprio 1
	v_mfma_f32_16x16x32_bf16 v[76:79], v[148:151], v[196:199], v[76:79]
	v_mfma_f32_16x16x32_bf16 v[72:75], v[172:175], v[196:199], v[72:75]
	v_mfma_f32_16x16x32_bf16 v[68:71], v[148:151], v[204:207], v[68:71]
	v_mfma_f32_16x16x32_bf16 v[64:67], v[172:175], v[204:207], v[64:67]
	s_setprio 0
	s_barrier
	s_add_i32 s62, s68, s33
	v_lshl_add_u64 v[208:209], v[208:209], 0, s[42:43]
	s_mov_b32 m0, s62
	ds_read_b128 v[176:179], v216 offset:49152
	ds_read_b128 v[180:183], v216 offset:50176
	ds_read_b128 v[184:187], v216 offset:51200
	ds_read_b128 v[188:191], v216 offset:52224
	ds_read_b128 v[192:195], v216 offset:53248
	ds_read_b128 v[196:199], v216 offset:54272
	ds_read_b128 v[200:203], v216 offset:55296
	ds_read_b128 v[204:207], v216 offset:56320
	global_load_lds_dwordx4 v[208:209], off
	s_add_i32 m0, s62, 0x2000
	s_add_u32 s6, s6, 0x40080
	v_lshl_add_u64 v[208:209], v[220:221], 0, s[42:43]
	s_addc_u32 s7, s7, 0
	s_add_i32 s62, s83, s33
	global_load_lds_dwordx4 v[208:209], off
	v_lshl_add_u64 v[208:209], s[6:7], 0, v[156:157]
	s_mov_b32 m0, s62
	s_nop 0
	global_load_lds_dwordx4 v[208:209], off
	v_lshl_add_u64 v[208:209], s[6:7], 0, v[152:153]
	s_add_i32 m0, s62, 0x2000
	s_nop 0
	global_load_lds_dwordx4 v[208:209], off
	v_lshl_add_u64 v[208:209], v[222:223], 0, s[42:43]
	s_mov_b32 m0, s75
	s_nop 0
	global_load_lds_dwordx4 v[208:209], off
	v_lshl_add_u64 v[208:209], v[224:225], 0, s[42:43]
	s_mov_b32 m0, s76
	s_nop 0
	global_load_lds_dwordx4 v[208:209], off
	s_waitcnt vmcnt(8)
	s_waitcnt lgkmcnt(0)
	s_barrier
	s_setprio 1
	s_waitcnt lgkmcnt(0)
	v_mfma_f32_16x16x32_bf16 v[60:63], v[128:131], v[176:179], v[60:63]
	v_mfma_f32_16x16x32_bf16 v[56:59], v[136:139], v[176:179], v[56:59]
	v_mfma_f32_16x16x32_bf16 v[52:55], v[128:131], v[184:187], v[52:55]
	v_mfma_f32_16x16x32_bf16 v[48:51], v[136:139], v[184:187], v[48:51]
	s_setprio 0
	s_setprio 1
	v_mfma_f32_16x16x32_bf16 v[40:43], v[128:131], v[192:195], v[40:43]
	v_mfma_f32_16x16x32_bf16 v[32:35], v[136:139], v[192:195], v[32:35]
	v_mfma_f32_16x16x32_bf16 v[20:23], v[128:131], v[200:203], v[20:23]
	v_mfma_f32_16x16x32_bf16 v[16:19], v[136:139], v[200:203], v[16:19]
	s_setprio 0
	s_setprio 1
	v_mfma_f32_16x16x32_bf16 v[60:63], v[132:135], v[180:183], v[60:63]
	v_mfma_f32_16x16x32_bf16 v[56:59], v[140:143], v[180:183], v[56:59]
	v_mfma_f32_16x16x32_bf16 v[52:55], v[132:135], v[188:191], v[52:55]
	v_mfma_f32_16x16x32_bf16 v[48:51], v[140:143], v[188:191], v[48:51]
	s_setprio 0
	s_setprio 1
	v_mfma_f32_16x16x32_bf16 v[40:43], v[132:135], v[196:199], v[40:43]
	v_mfma_f32_16x16x32_bf16 v[32:35], v[140:143], v[196:199], v[32:35]
	v_mfma_f32_16x16x32_bf16 v[20:23], v[132:135], v[204:207], v[20:23]
	v_mfma_f32_16x16x32_bf16 v[16:19], v[140:143], v[204:207], v[16:19]
	s_setprio 0
	s_setprio 1
	v_mfma_f32_16x16x32_bf16 v[44:47], v[144:147], v[176:179], v[44:47]
	v_mfma_f32_16x16x32_bf16 v[36:39], v[168:171], v[176:179], v[36:39]
	v_mfma_f32_16x16x32_bf16 v[28:31], v[144:147], v[184:187], v[28:31]
	v_mfma_f32_16x16x32_bf16 v[24:27], v[168:171], v[184:187], v[24:27]
	s_setprio 0
	s_setprio 1
	v_mfma_f32_16x16x32_bf16 v[12:15], v[144:147], v[192:195], v[12:15]
	v_mfma_f32_16x16x32_bf16 v[8:11], v[168:171], v[192:195], v[8:11]
	v_mfma_f32_16x16x32_bf16 v[4:7], v[144:147], v[200:203], v[4:7]
	v_mfma_f32_16x16x32_bf16 v[0:3], v[168:171], v[200:203], v[0:3]
	s_setprio 0
	s_setprio 1
	v_mfma_f32_16x16x32_bf16 v[44:47], v[148:151], v[180:183], v[44:47]
	v_mfma_f32_16x16x32_bf16 v[36:39], v[172:175], v[180:183], v[36:39]
	v_mfma_f32_16x16x32_bf16 v[28:31], v[148:151], v[188:191], v[28:31]
	v_mfma_f32_16x16x32_bf16 v[24:27], v[172:175], v[188:191], v[24:27]
	s_setprio 0
	s_setprio 1
	v_mfma_f32_16x16x32_bf16 v[12:15], v[148:151], v[196:199], v[12:15]
	v_mfma_f32_16x16x32_bf16 v[8:11], v[172:175], v[196:199], v[8:11]
	v_mfma_f32_16x16x32_bf16 v[4:7], v[148:151], v[204:207], v[4:7]
	v_mfma_f32_16x16x32_bf16 v[0:3], v[172:175], v[204:207], v[0:3]
	s_setprio 0
	s_barrier
	s_add_i32 s57, s57, 2
	s_add_u32 s4, s4, 0x100
	s_addc_u32 s5, s5, 0
	s_add_u32 s28, s28, 0x100
	s_addc_u32 s55, s55, 0
	s_cmp_gt_u32 s57, 13
	s_cbranch_scc0 .LBB0_704
	s_and_b64 vcc, exec, s[44:45]
	s_cbranch_vccz .LBB0_707
	s_barrier

.LBB0_862:
	ds_read_b128 v[152:155], v159
	ds_read_b128 v[164:167], v159 offset:1024
	ds_read_b128 v[168:171], v159 offset:2048
	ds_read_b128 v[172:175], v159 offset:3072
	ds_read_b128 v[176:179], v160
	ds_read_b128 v[180:183], v160 offset:1024
	ds_read_b128 v[184:187], v160 offset:2048
	ds_read_b128 v[188:191], v160 offset:3072
	s_add_u32 s4, s40, 0x100
	s_addc_u32 s5, s41, 0
	s_cmp_eq_u32 s58, 2
	s_cselect_b32 s45, s35, s5
	s_cselect_b32 s44, s34, s4
	s_cselect_b32 s43, s37, s57
	s_cselect_b32 s42, s36, s56
	v_lshl_add_u64 v[156:157], s[40:41], 0, v[144:145]
	s_add_i32 m0, s11, 0xc000
	ds_read_b128 v[192:195], v161
	ds_read_b128 v[196:199], v161 offset:1024
	ds_read_b128 v[200:203], v161 offset:2048
	ds_read_b128 v[204:207], v161 offset:3072
	ds_read_b128 v[212:215], v161 offset:4096
	ds_read_b128 v[216:219], v161 offset:5120
	ds_read_b128 v[220:223], v161 offset:6144
	ds_read_b128 v[224:227], v161 offset:7168
	global_load_lds_dwordx4 v[156:157], off
	v_lshl_add_u64 v[156:157], s[40:41], 0, v[146:147]
	s_add_i32 m0, s11, 0xe000
	s_nop 0
	global_load_lds_dwordx4 v[156:157], off
	s_waitcnt vmcnt(8)
	s_waitcnt lgkmcnt(0)
	s_barrier
	s_setprio 1
	s_waitcnt lgkmcnt(0)
	v_mfma_f32_16x16x32_bf16 v[124:127], v[152:155], v[192:195], v[124:127]
	v_mfma_f32_16x16x32_bf16 v[120:123], v[168:171], v[192:195], v[120:123]
	v_mfma_f32_16x16x32_bf16 v[108:111], v[152:155], v[200:203], v[108:111]
	v_mfma_f32_16x16x32_bf16 v[104:107], v[168:171], v[200:203], v[104:107]
	s_setprio 0
	s_setprio 1
	v_mfma_f32_16x16x32_bf16 v[92:95], v[152:155], v[212:215], v[92:95]
	v_mfma_f32_16x16x32_bf16 v[88:91], v[168:171], v[212:215], v[88:91]
	v_mfma_f32_16x16x32_bf16 v[76:79], v[152:155], v[220:223], v[76:79]
	v_mfma_f32_16x16x32_bf16 v[72:75], v[168:171], v[220:223], v[72:75]
	s_setprio 0
	s_setprio 1
	v_mfma_f32_16x16x32_bf16 v[124:127], v[164:167], v[196:199], v[124:127]
	v_mfma_f32_16x16x32_bf16 v[120:123], v[172:175], v[196:199], v[120:123]
	v_mfma_f32_16x16x32_bf16 v[108:111], v[164:167], v[204:207], v[108:111]
	v_mfma_f32_16x16x32_bf16 v[104:107], v[172:175], v[204:207], v[104:107]
	s_setprio 0
	s_setprio 1
	v_mfma_f32_16x16x32_bf16 v[92:95], v[164:167], v[216:219], v[92:95]
	v_mfma_f32_16x16x32_bf16 v[88:91], v[172:175], v[216:219], v[88:91]
	v_mfma_f32_16x16x32_bf16 v[76:79], v[164:167], v[224:227], v[76:79]
	v_mfma_f32_16x16x32_bf16 v[72:75], v[172:175], v[224:227], v[72:75]
	s_setprio 0
	s_setprio 1
	v_mfma_f32_16x16x32_bf16 v[116:119], v[176:179], v[192:195], v[116:119]
	v_mfma_f32_16x16x32_bf16 v[112:115], v[184:187], v[192:195], v[112:115]
	v_mfma_f32_16x16x32_bf16 v[100:103], v[176:179], v[200:203], v[100:103]
	v_mfma_f32_16x16x32_bf16 v[96:99], v[184:187], v[200:203], v[96:99]
	s_setprio 0
	s_setprio 1
	v_mfma_f32_16x16x32_bf16 v[84:87], v[176:179], v[212:215], v[84:87]
	v_mfma_f32_16x16x32_bf16 v[80:83], v[184:187], v[212:215], v[80:83]
	v_mfma_f32_16x16x32_bf16 v[68:71], v[176:179], v[220:223], v[68:71]
	v_mfma_f32_16x16x32_bf16 v[64:67], v[184:187], v[220:223], v[64:67]
	s_setprio 0
	s_setprio 1
	v_mfma_f32_16x16x32_bf16 v[116:119], v[180:183], v[196:199], v[116:119]
	v_mfma_f32_16x16x32_bf16 v[112:115], v[188:191], v[196:199], v[112:115]
	v_mfma_f32_16x16x32_bf16 v[100:103], v[180:183], v[204:207], v[100:103]
	v_mfma_f32_16x16x32_bf16 v[96:99], v[188:191], v[204:207], v[96:99]
	s_setprio 0
	s_setprio 1
	v_mfma_f32_16x16x32_bf16 v[84:87], v[180:183], v[216:219], v[84:87]
	v_mfma_f32_16x16x32_bf16 v[80:83], v[188:191], v[216:219], v[80:83]
	v_mfma_f32_16x16x32_bf16 v[68:71], v[180:183], v[224:227], v[68:71]
	v_mfma_f32_16x16x32_bf16 v[64:67], v[188:191], v[224:227], v[64:67]
	s_setprio 0
	s_barrier
	s_add_i32 s40, s48, s10
	v_lshl_add_u64 v[156:157], s[42:43], 0, v[130:131]
	s_mov_b32 m0, s40
	ds_read_b128 v[192:195], v161 offset:16384
	ds_read_b128 v[196:199], v161 offset:17408
	ds_read_b128 v[200:203], v161 offset:18432
	ds_read_b128 v[204:207], v161 offset:19456
	ds_read_b128 v[212:215], v161 offset:20480
	ds_read_b128 v[216:219], v161 offset:21504
	ds_read_b128 v[220:223], v161 offset:22528
	ds_read_b128 v[224:227], v161 offset:23552
	global_load_lds_dwordx4 v[156:157], off
	s_add_i32 m0, s40, 0x2000
	s_add_u32 s40, s42, 0x18000
	v_lshl_add_u64 v[208:209], s[42:43], 0, v[134:135]
	s_addc_u32 s41, s43, 0
	s_add_i32 s59, s49, s10
	global_load_lds_dwordx4 v[208:209], off
	v_lshl_add_u64 v[228:229], s[40:41], 0, v[130:131]
	s_mov_b32 m0, s59
	v_lshl_add_u64 v[230:231], s[44:45], 0, v[132:133]
	global_load_lds_dwordx4 v[228:229], off
	v_lshl_add_u64 v[228:229], s[40:41], 0, v[134:135]
	s_add_i32 m0, s59, 0x2000
	s_nop 0
	global_load_lds_dwordx4 v[228:229], off
	v_lshl_add_u64 v[228:229], s[44:45], 0, v[128:129]
	s_mov_b32 m0, s11
	s_nop 0
	global_load_lds_dwordx4 v[228:229], off
	s_mov_b32 m0, s14
	s_nop 0
	global_load_lds_dwordx4 v[230:231], off
	s_waitcnt vmcnt(8)
	s_waitcnt lgkmcnt(0)
	s_barrier
	s_setprio 1
	s_waitcnt lgkmcnt(0)
	v_mfma_f32_16x16x32_bf16 v[60:63], v[152:155], v[192:195], v[60:63]
	v_mfma_f32_16x16x32_bf16 v[56:59], v[168:171], v[192:195], v[56:59]
	v_mfma_f32_16x16x32_bf16 v[44:47], v[152:155], v[200:203], v[44:47]
	v_mfma_f32_16x16x32_bf16 v[40:43], v[168:171], v[200:203], v[40:43]
	s_setprio 0
	s_setprio 1
	v_mfma_f32_16x16x32_bf16 v[28:31], v[152:155], v[212:215], v[28:31]
	v_mfma_f32_16x16x32_bf16 v[24:27], v[168:171], v[212:215], v[24:27]
	v_mfma_f32_16x16x32_bf16 v[12:15], v[152:155], v[220:223], v[12:15]
	v_mfma_f32_16x16x32_bf16 v[8:11], v[168:171], v[220:223], v[8:11]
	s_setprio 0
	s_setprio 1
	v_mfma_f32_16x16x32_bf16 v[60:63], v[164:167], v[196:199], v[60:63]
	v_mfma_f32_16x16x32_bf16 v[56:59], v[172:175], v[196:199], v[56:59]
	v_mfma_f32_16x16x32_bf16 v[44:47], v[164:167], v[204:207], v[44:47]
	v_mfma_f32_16x16x32_bf16 v[40:43], v[172:175], v[204:207], v[40:43]
	s_setprio 0
	s_setprio 1
	v_mfma_f32_16x16x32_bf16 v[28:31], v[164:167], v[216:219], v[28:31]
	v_mfma_f32_16x16x32_bf16 v[24:27], v[172:175], v[216:219], v[24:27]
	v_mfma_f32_16x16x32_bf16 v[12:15], v[164:167], v[224:227], v[12:15]
	v_mfma_f32_16x16x32_bf16 v[8:11], v[172:175], v[224:227], v[8:11]
	s_setprio 0
	s_setprio 1
	v_mfma_f32_16x16x32_bf16 v[52:55], v[176:179], v[192:195], v[52:55]
	v_mfma_f32_16x16x32_bf16 v[48:51], v[184:187], v[192:195], v[48:51]
	v_mfma_f32_16x16x32_bf16 v[36:39], v[176:179], v[200:203], v[36:39]
	v_mfma_f32_16x16x32_bf16 v[32:35], v[184:187], v[200:203], v[32:35]
	s_setprio 0
	s_setprio 1
	v_mfma_f32_16x16x32_bf16 v[20:23], v[176:179], v[212:215], v[20:23]
	v_mfma_f32_16x16x32_bf16 v[16:19], v[184:187], v[212:215], v[16:19]
	v_mfma_f32_16x16x32_bf16 v[4:7], v[176:179], v[220:223], v[4:7]
	v_mfma_f32_16x16x32_bf16 v[0:3], v[184:187], v[220:223], v[0:3]
	s_setprio 0
	s_setprio 1
	v_mfma_f32_16x16x32_bf16 v[52:55], v[180:183], v[196:199], v[52:55]
	v_mfma_f32_16x16x32_bf16 v[48:51], v[188:191], v[196:199], v[48:51]
	v_mfma_f32_16x16x32_bf16 v[36:39], v[180:183], v[204:207], v[36:39]
	v_mfma_f32_16x16x32_bf16 v[32:35], v[188:191], v[204:207], v[32:35]
	s_setprio 0
	s_setprio 1
	v_mfma_f32_16x16x32_bf16 v[20:23], v[180:183], v[216:219], v[20:23]
	v_mfma_f32_16x16x32_bf16 v[16:19], v[188:191], v[216:219], v[16:19]
	v_mfma_f32_16x16x32_bf16 v[4:7], v[180:183], v[224:227], v[4:7]
	v_mfma_f32_16x16x32_bf16 v[0:3], v[188:191], v[224:227], v[0:3]
	s_setprio 0
	s_barrier
	s_add_i32 s59, 0, 0x18000
	v_add_u32_e32 v163, s59, v158
	s_add_i32 s60, 0, 0x1c000
	ds_read_b128 v[152:155], v163
	ds_read_b128 v[164:167], v163 offset:1024
	ds_read_b128 v[168:171], v163 offset:2048
	ds_read_b128 v[172:175], v163 offset:3072
	v_add_u32_e32 v163, s60, v158
	ds_read_b128 v[176:179], v163
	ds_read_b128 v[180:183], v163 offset:1024
	ds_read_b128 v[184:187], v163 offset:2048
	ds_read_b128 v[188:191], v163 offset:3072
	s_add_u32 s40, s44, 0x18000
	s_addc_u32 s41, s45, 0
	s_mov_b32 m0, s15
	v_lshl_add_u64 v[232:233], s[40:41], 0, v[128:129]
	ds_read_b128 v[192:195], v161 offset:32768
	ds_read_b128 v[196:199], v161 offset:33792
	ds_read_b128 v[200:203], v161 offset:34816
	ds_read_b128 v[204:207], v161 offset:35840
	ds_read_b128 v[212:215], v161 offset:36864
	ds_read_b128 v[216:219], v161 offset:37888
	ds_read_b128 v[220:223], v161 offset:38912
	ds_read_b128 v[224:227], v161 offset:39936
	global_load_lds_dwordx4 v[232:233], off
	v_lshl_add_u64 v[232:233], s[40:41], 0, v[132:133]
	s_mov_b32 m0, s28
	s_nop 0
	global_load_lds_dwordx4 v[232:233], off
	s_waitcnt vmcnt(8)
	s_waitcnt lgkmcnt(0)
	s_barrier
	s_setprio 1
	s_waitcnt lgkmcnt(0)
	v_mfma_f32_16x16x32_bf16 v[124:127], v[152:155], v[192:195], v[124:127]
	v_mfma_f32_16x16x32_bf16 v[120:123], v[168:171], v[192:195], v[120:123]
	v_mfma_f32_16x16x32_bf16 v[108:111], v[152:155], v[200:203], v[108:111]
	v_mfma_f32_16x16x32_bf16 v[104:107], v[168:171], v[200:203], v[104:107]
	s_setprio 0
	s_setprio 1
	v_mfma_f32_16x16x32_bf16 v[92:95], v[152:155], v[212:215], v[92:95]
	v_mfma_f32_16x16x32_bf16 v[88:91], v[168:171], v[212:215], v[88:91]
	v_mfma_f32_16x16x32_bf16 v[76:79], v[152:155], v[220:223], v[76:79]
	v_mfma_f32_16x16x32_bf16 v[72:75], v[168:171], v[220:223], v[72:75]
	s_setprio 0
	s_setprio 1
	v_mfma_f32_16x16x32_bf16 v[124:127], v[164:167], v[196:199], v[124:127]
	v_mfma_f32_16x16x32_bf16 v[120:123], v[172:175], v[196:199], v[120:123]
	v_mfma_f32_16x16x32_bf16 v[108:111], v[164:167], v[204:207], v[108:111]
	v_mfma_f32_16x16x32_bf16 v[104:107], v[172:175], v[204:207], v[104:107]
	s_setprio 0
	s_setprio 1
	v_mfma_f32_16x16x32_bf16 v[92:95], v[164:167], v[216:219], v[92:95]
	v_mfma_f32_16x16x32_bf16 v[88:91], v[172:175], v[216:219], v[88:91]
	v_mfma_f32_16x16x32_bf16 v[76:79], v[164:167], v[224:227], v[76:79]
	v_mfma_f32_16x16x32_bf16 v[72:75], v[172:175], v[224:227], v[72:75]
	s_setprio 0
	s_setprio 1
	v_mfma_f32_16x16x32_bf16 v[116:119], v[176:179], v[192:195], v[116:119]
	v_mfma_f32_16x16x32_bf16 v[112:115], v[184:187], v[192:195], v[112:115]
	v_mfma_f32_16x16x32_bf16 v[100:103], v[176:179], v[200:203], v[100:103]
	v_mfma_f32_16x16x32_bf16 v[96:99], v[184:187], v[200:203], v[96:99]
	s_setprio 0
	s_setprio 1
	v_mfma_f32_16x16x32_bf16 v[84:87], v[176:179], v[212:215], v[84:87]
	v_mfma_f32_16x16x32_bf16 v[80:83], v[184:187], v[212:215], v[80:83]
	v_mfma_f32_16x16x32_bf16 v[68:71], v[176:179], v[220:223], v[68:71]
	v_mfma_f32_16x16x32_bf16 v[64:67], v[184:187], v[220:223], v[64:67]
	s_setprio 0
	s_setprio 1
	v_mfma_f32_16x16x32_bf16 v[116:119], v[180:183], v[196:199], v[116:119]
	v_mfma_f32_16x16x32_bf16 v[112:115], v[188:191], v[196:199], v[112:115]
	v_mfma_f32_16x16x32_bf16 v[100:103], v[180:183], v[204:207], v[100:103]
	v_mfma_f32_16x16x32_bf16 v[96:99], v[188:191], v[204:207], v[96:99]
	s_setprio 0
	s_setprio 1
	v_mfma_f32_16x16x32_bf16 v[84:87], v[180:183], v[216:219], v[84:87]
	v_mfma_f32_16x16x32_bf16 v[80:83], v[188:191], v[216:219], v[80:83]
	v_mfma_f32_16x16x32_bf16 v[68:71], v[180:183], v[224:227], v[68:71]
	v_mfma_f32_16x16x32_bf16 v[64:67], v[188:191], v[224:227], v[64:67]
	s_setprio 0
	s_barrier
	s_add_i32 s40, s59, s10
	v_lshl_add_u64 v[156:157], v[156:157], 0, s[8:9]
	s_mov_b32 m0, s40
	ds_read_b128 v[192:195], v161 offset:49152
	ds_read_b128 v[196:199], v161 offset:50176
	ds_read_b128 v[200:203], v161 offset:51200
	ds_read_b128 v[204:207], v161 offset:52224
	ds_read_b128 v[212:215], v161 offset:53248
	ds_read_b128 v[216:219], v161 offset:54272
	ds_read_b128 v[220:223], v161 offset:55296
	ds_read_b128 v[224:227], v161 offset:56320
	global_load_lds_dwordx4 v[156:157], off
	s_add_i32 m0, s40, 0x2000
	s_add_u32 s40, s42, 0x18080
	v_lshl_add_u64 v[156:157], v[208:209], 0, s[8:9]
	s_addc_u32 s41, s43, 0
	s_add_i32 s42, s60, s10
	global_load_lds_dwordx4 v[156:157], off
	v_lshl_add_u64 v[156:157], s[40:41], 0, v[130:131]
	s_mov_b32 m0, s42
	s_nop 0
	global_load_lds_dwordx4 v[156:157], off
	v_lshl_add_u64 v[156:157], s[40:41], 0, v[134:135]
	s_add_i32 m0, s42, 0x2000
	s_nop 0
	global_load_lds_dwordx4 v[156:157], off
	v_lshl_add_u64 v[156:157], v[228:229], 0, s[8:9]
	s_mov_b32 m0, s33
	s_nop 0
	global_load_lds_dwordx4 v[156:157], off
	v_lshl_add_u64 v[156:157], v[230:231], 0, s[8:9]
	s_mov_b32 m0, s46
	s_nop 0
	global_load_lds_dwordx4 v[156:157], off
	s_waitcnt vmcnt(8)
	s_waitcnt lgkmcnt(0)
	s_barrier
	s_setprio 1
	s_waitcnt lgkmcnt(0)
	v_mfma_f32_16x16x32_bf16 v[60:63], v[152:155], v[192:195], v[60:63]
	v_mfma_f32_16x16x32_bf16 v[56:59], v[168:171], v[192:195], v[56:59]
	v_mfma_f32_16x16x32_bf16 v[44:47], v[152:155], v[200:203], v[44:47]
	v_mfma_f32_16x16x32_bf16 v[40:43], v[168:171], v[200:203], v[40:43]
	s_setprio 0
	s_setprio 1
	v_mfma_f32_16x16x32_bf16 v[28:31], v[152:155], v[212:215], v[28:31]
	v_mfma_f32_16x16x32_bf16 v[24:27], v[168:171], v[212:215], v[24:27]
	v_mfma_f32_16x16x32_bf16 v[12:15], v[152:155], v[220:223], v[12:15]
	v_mfma_f32_16x16x32_bf16 v[8:11], v[168:171], v[220:223], v[8:11]
	s_setprio 0
	s_setprio 1
	v_mfma_f32_16x16x32_bf16 v[60:63], v[164:167], v[196:199], v[60:63]
	v_mfma_f32_16x16x32_bf16 v[56:59], v[172:175], v[196:199], v[56:59]
	v_mfma_f32_16x16x32_bf16 v[44:47], v[164:167], v[204:207], v[44:47]
	v_mfma_f32_16x16x32_bf16 v[40:43], v[172:175], v[204:207], v[40:43]
	s_setprio 0
	s_setprio 1
	v_mfma_f32_16x16x32_bf16 v[28:31], v[164:167], v[216:219], v[28:31]
	v_mfma_f32_16x16x32_bf16 v[24:27], v[172:175], v[216:219], v[24:27]
	v_mfma_f32_16x16x32_bf16 v[12:15], v[164:167], v[224:227], v[12:15]
	v_mfma_f32_16x16x32_bf16 v[8:11], v[172:175], v[224:227], v[8:11]
	s_setprio 0
	s_setprio 1
	v_mfma_f32_16x16x32_bf16 v[52:55], v[176:179], v[192:195], v[52:55]
	v_mfma_f32_16x16x32_bf16 v[48:51], v[184:187], v[192:195], v[48:51]
	v_mfma_f32_16x16x32_bf16 v[36:39], v[176:179], v[200:203], v[36:39]
	v_mfma_f32_16x16x32_bf16 v[32:35], v[184:187], v[200:203], v[32:35]
	s_setprio 0
	s_setprio 1
	v_mfma_f32_16x16x32_bf16 v[20:23], v[176:179], v[212:215], v[20:23]
	v_mfma_f32_16x16x32_bf16 v[16:19], v[184:187], v[212:215], v[16:19]
	v_mfma_f32_16x16x32_bf16 v[4:7], v[176:179], v[220:223], v[4:7]
	v_mfma_f32_16x16x32_bf16 v[0:3], v[184:187], v[220:223], v[0:3]
	s_setprio 0
	s_setprio 1
	v_mfma_f32_16x16x32_bf16 v[52:55], v[180:183], v[196:199], v[52:55]
	v_mfma_f32_16x16x32_bf16 v[48:51], v[188:191], v[196:199], v[48:51]
	v_mfma_f32_16x16x32_bf16 v[36:39], v[180:183], v[204:207], v[36:39]
	v_mfma_f32_16x16x32_bf16 v[32:35], v[188:191], v[204:207], v[32:35]
	s_setprio 0
	s_setprio 1
	v_mfma_f32_16x16x32_bf16 v[20:23], v[180:183], v[216:219], v[20:23]
	v_mfma_f32_16x16x32_bf16 v[16:19], v[188:191], v[216:219], v[16:19]
	v_mfma_f32_16x16x32_bf16 v[4:7], v[180:183], v[224:227], v[4:7]
	v_mfma_f32_16x16x32_bf16 v[0:3], v[188:191], v[224:227], v[0:3]
	s_setprio 0
	s_barrier
	s_add_i32 s58, s58, 2
	s_add_u32 s56, s56, 0x100
	s_addc_u32 s57, s57, 0
	s_cmp_gt_u32 s58, 3
	s_mov_b64 s[40:41], s[4:5]
	s_cbranch_scc0 .LBB0_862
	s_and_b64 vcc, exec, s[20:21]
	s_cbranch_vccz .LBB0_865
	s_barrier

.LBB0_894:
	s_add_u32 s46, s34, s40
	s_addc_u32 s47, s35, s41
	s_add_u32 s44, s46, 0x100
	s_addc_u32 s45, s47, 0
	s_and_b64 s[42:43], s[38:39], exec
	s_cselect_b32 s43, s19, s45
	s_cselect_b32 s42, s53, s44
	s_add_u32 s40, s30, s40
	s_addc_u32 s41, s31, s41
	s_add_u32 s40, s40, 0x100
	s_addc_u32 s41, s41, 0
	s_and_b64 s[38:39], s[38:39], exec
	s_cselect_b32 s45, s9, s41
	s_cselect_b32 s44, s54, s40
	s_add_u32 s48, s46, 0x10080
	ds_read_b128 v[144:147], v150
	ds_read_b128 v[154:157], v150 offset:1024
	ds_read_b128 v[158:161], v150 offset:2048
	ds_read_b128 v[162:165], v150 offset:3072
	ds_read_b128 v[166:169], v151
	ds_read_b128 v[170:173], v151 offset:1024
	ds_read_b128 v[174:177], v151 offset:2048
	ds_read_b128 v[178:181], v151 offset:3072
	s_addc_u32 s49, s47, 0
	s_add_i32 s64, s50, s10
	s_add_i32 m0, s11, 0xc000
	s_add_i32 s65, s11, 0xe000
	s_add_i32 s61, s64, 0x2000
	s_add_u32 s46, s44, 0x10000
	s_addc_u32 s47, s45, 0
	s_add_i32 s63, s51, s10
	s_add_i32 s62, s63, 0x2000
	s_add_i32 s60, 0, 0x18000
	s_add_i32 s59, 0, 0x1c000
	s_add_u32 s40, s42, 0x10000
	s_addc_u32 s41, s43, 0
	s_add_i32 s58, s60, s10
	s_add_i32 s56, s58, 0x2000
	s_add_u32 s38, s44, 0x10080
	s_addc_u32 s39, s45, 0
	s_add_i32 s57, s59, s10
	s_add_i32 s55, s57, 0x2000
	v_lshl_add_u64 v[216:217], s[48:49], 0, v[134:135]
	ds_read_b128 v[182:185], v152
	ds_read_b128 v[186:189], v152 offset:1024
	ds_read_b128 v[190:193], v152 offset:2048
	ds_read_b128 v[194:197], v152 offset:3072
	ds_read_b128 v[198:201], v152 offset:4096
	ds_read_b128 v[202:205], v152 offset:5120
	ds_read_b128 v[206:209], v152 offset:6144
	ds_read_b128 v[212:215], v152 offset:7168
	global_load_lds_dwordx4 v[216:217], off
	v_lshl_add_u64 v[216:217], s[48:49], 0, v[130:131]
	s_mov_b32 m0, s65
	s_nop 0
	global_load_lds_dwordx4 v[216:217], off
	s_waitcnt vmcnt(8)
	s_waitcnt lgkmcnt(0)
	s_barrier
	s_setprio 1
	s_waitcnt lgkmcnt(0)
	v_mfma_f32_16x16x32_bf16 v[124:127], v[144:147], v[182:185], v[124:127]
	v_mfma_f32_16x16x32_bf16 v[120:123], v[158:161], v[182:185], v[120:123]
	v_mfma_f32_16x16x32_bf16 v[108:111], v[144:147], v[190:193], v[108:111]
	v_mfma_f32_16x16x32_bf16 v[104:107], v[158:161], v[190:193], v[104:107]
	s_setprio 0
	s_setprio 1
	v_mfma_f32_16x16x32_bf16 v[92:95], v[144:147], v[198:201], v[92:95]
	v_mfma_f32_16x16x32_bf16 v[88:91], v[158:161], v[198:201], v[88:91]
	v_mfma_f32_16x16x32_bf16 v[76:79], v[144:147], v[206:209], v[76:79]
	v_mfma_f32_16x16x32_bf16 v[72:75], v[158:161], v[206:209], v[72:75]
	s_setprio 0
	s_setprio 1
	v_mfma_f32_16x16x32_bf16 v[124:127], v[154:157], v[186:189], v[124:127]
	v_mfma_f32_16x16x32_bf16 v[120:123], v[162:165], v[186:189], v[120:123]
	v_mfma_f32_16x16x32_bf16 v[108:111], v[154:157], v[194:197], v[108:111]
	v_mfma_f32_16x16x32_bf16 v[104:107], v[162:165], v[194:197], v[104:107]
	s_setprio 0
	s_setprio 1
	v_mfma_f32_16x16x32_bf16 v[92:95], v[154:157], v[202:205], v[92:95]
	v_mfma_f32_16x16x32_bf16 v[88:91], v[162:165], v[202:205], v[88:91]
	v_mfma_f32_16x16x32_bf16 v[76:79], v[154:157], v[212:215], v[76:79]
	v_mfma_f32_16x16x32_bf16 v[72:75], v[162:165], v[212:215], v[72:75]
	s_setprio 0
	s_setprio 1
	v_mfma_f32_16x16x32_bf16 v[116:119], v[166:169], v[182:185], v[116:119]
	v_mfma_f32_16x16x32_bf16 v[112:115], v[174:177], v[182:185], v[112:115]
	v_mfma_f32_16x16x32_bf16 v[100:103], v[166:169], v[190:193], v[100:103]
	v_mfma_f32_16x16x32_bf16 v[96:99], v[174:177], v[190:193], v[96:99]
	s_setprio 0
	s_setprio 1
	v_mfma_f32_16x16x32_bf16 v[84:87], v[166:169], v[198:201], v[84:87]
	v_mfma_f32_16x16x32_bf16 v[80:83], v[174:177], v[198:201], v[80:83]
	v_mfma_f32_16x16x32_bf16 v[68:71], v[166:169], v[206:209], v[68:71]
	v_mfma_f32_16x16x32_bf16 v[64:67], v[174:177], v[206:209], v[64:67]
	s_setprio 0
	s_setprio 1
	v_mfma_f32_16x16x32_bf16 v[116:119], v[170:173], v[186:189], v[116:119]
	v_mfma_f32_16x16x32_bf16 v[112:115], v[178:181], v[186:189], v[112:115]
	v_mfma_f32_16x16x32_bf16 v[100:103], v[170:173], v[194:197], v[100:103]
	v_mfma_f32_16x16x32_bf16 v[96:99], v[178:181], v[194:197], v[96:99]
	s_setprio 0
	s_setprio 1
	v_mfma_f32_16x16x32_bf16 v[84:87], v[170:173], v[202:205], v[84:87]
	v_mfma_f32_16x16x32_bf16 v[80:83], v[178:181], v[202:205], v[80:83]
	v_mfma_f32_16x16x32_bf16 v[68:71], v[170:173], v[212:215], v[68:71]
	v_mfma_f32_16x16x32_bf16 v[64:67], v[178:181], v[212:215], v[64:67]
	s_setprio 0
	s_barrier
	s_mov_b32 m0, s64
	v_lshl_add_u64 v[216:217], s[44:45], 0, v[132:133]
	ds_read_b128 v[182:185], v152 offset:16384
	ds_read_b128 v[186:189], v152 offset:17408
	ds_read_b128 v[190:193], v152 offset:18432
	ds_read_b128 v[194:197], v152 offset:19456
	ds_read_b128 v[198:201], v152 offset:20480
	ds_read_b128 v[202:205], v152 offset:21504
	ds_read_b128 v[206:209], v152 offset:22528
	ds_read_b128 v[212:215], v152 offset:23552
	global_load_lds_dwordx4 v[216:217], off
	v_lshl_add_u64 v[218:219], s[44:45], 0, v[128:129]
	s_mov_b32 m0, s61
	v_lshl_add_u64 v[220:221], s[46:47], 0, v[132:133]
	global_load_lds_dwordx4 v[218:219], off
	s_mov_b32 m0, s63
	v_lshl_add_u64 v[222:223], s[42:43], 0, v[130:131]
	global_load_lds_dwordx4 v[220:221], off
	v_lshl_add_u64 v[220:221], s[46:47], 0, v[128:129]
	s_mov_b32 m0, s62
	s_nop 0
	global_load_lds_dwordx4 v[220:221], off
	v_lshl_add_u64 v[220:221], s[42:43], 0, v[134:135]
	s_mov_b32 m0, s11
	s_nop 0
	global_load_lds_dwordx4 v[220:221], off
	s_mov_b32 m0, s14
	s_nop 0
	global_load_lds_dwordx4 v[222:223], off
	s_waitcnt vmcnt(8)
	s_waitcnt lgkmcnt(0)
	s_barrier
	s_setprio 1
	s_waitcnt lgkmcnt(0)
	v_mfma_f32_16x16x32_bf16 v[60:63], v[144:147], v[182:185], v[60:63]
	v_mfma_f32_16x16x32_bf16 v[56:59], v[158:161], v[182:185], v[56:59]
	v_mfma_f32_16x16x32_bf16 v[44:47], v[144:147], v[190:193], v[44:47]
	v_mfma_f32_16x16x32_bf16 v[40:43], v[158:161], v[190:193], v[40:43]
	s_setprio 0
	s_setprio 1
	v_mfma_f32_16x16x32_bf16 v[28:31], v[144:147], v[198:201], v[28:31]
	v_mfma_f32_16x16x32_bf16 v[24:27], v[158:161], v[198:201], v[24:27]
	v_mfma_f32_16x16x32_bf16 v[12:15], v[144:147], v[206:209], v[12:15]
	v_mfma_f32_16x16x32_bf16 v[8:11], v[158:161], v[206:209], v[8:11]
	s_setprio 0
	s_setprio 1
	v_mfma_f32_16x16x32_bf16 v[60:63], v[154:157], v[186:189], v[60:63]
	v_mfma_f32_16x16x32_bf16 v[56:59], v[162:165], v[186:189], v[56:59]
	v_mfma_f32_16x16x32_bf16 v[44:47], v[154:157], v[194:197], v[44:47]
	v_mfma_f32_16x16x32_bf16 v[40:43], v[162:165], v[194:197], v[40:43]
	s_setprio 0
	s_setprio 1
	v_mfma_f32_16x16x32_bf16 v[28:31], v[154:157], v[202:205], v[28:31]
	v_mfma_f32_16x16x32_bf16 v[24:27], v[162:165], v[202:205], v[24:27]
	v_mfma_f32_16x16x32_bf16 v[12:15], v[154:157], v[212:215], v[12:15]
	v_mfma_f32_16x16x32_bf16 v[8:11], v[162:165], v[212:215], v[8:11]
	s_setprio 0
	s_setprio 1
	v_mfma_f32_16x16x32_bf16 v[52:55], v[166:169], v[182:185], v[52:55]
	v_mfma_f32_16x16x32_bf16 v[48:51], v[174:177], v[182:185], v[48:51]
	v_mfma_f32_16x16x32_bf16 v[36:39], v[166:169], v[190:193], v[36:39]
	v_mfma_f32_16x16x32_bf16 v[32:35], v[174:177], v[190:193], v[32:35]
	s_setprio 0
	s_setprio 1
	v_mfma_f32_16x16x32_bf16 v[20:23], v[166:169], v[198:201], v[20:23]
	v_mfma_f32_16x16x32_bf16 v[16:19], v[174:177], v[198:201], v[16:19]
	v_mfma_f32_16x16x32_bf16 v[4:7], v[166:169], v[206:209], v[4:7]
	v_mfma_f32_16x16x32_bf16 v[0:3], v[174:177], v[206:209], v[0:3]
	s_setprio 0
	s_setprio 1
	v_mfma_f32_16x16x32_bf16 v[52:55], v[170:173], v[186:189], v[52:55]
	v_mfma_f32_16x16x32_bf16 v[48:51], v[178:181], v[186:189], v[48:51]
	v_mfma_f32_16x16x32_bf16 v[36:39], v[170:173], v[194:197], v[36:39]
	v_mfma_f32_16x16x32_bf16 v[32:35], v[178:181], v[194:197], v[32:35]
	s_setprio 0
	s_setprio 1
	v_mfma_f32_16x16x32_bf16 v[20:23], v[170:173], v[202:205], v[20:23]
	v_mfma_f32_16x16x32_bf16 v[16:19], v[178:181], v[202:205], v[16:19]
	v_mfma_f32_16x16x32_bf16 v[4:7], v[170:173], v[212:215], v[4:7]
	v_mfma_f32_16x16x32_bf16 v[0:3], v[178:181], v[212:215], v[0:3]
	s_setprio 0
	s_barrier
	v_add_u32_e32 v162, s60, v149
	v_add_u32_e32 v178, s59, v149
	ds_read_b128 v[144:147], v162
	ds_read_b128 v[154:157], v162 offset:1024
	ds_read_b128 v[158:161], v162 offset:2048
	ds_read_b128 v[162:165], v162 offset:3072
	ds_read_b128 v[166:169], v178
	ds_read_b128 v[170:173], v178 offset:1024
	ds_read_b128 v[174:177], v178 offset:2048
	ds_read_b128 v[178:181], v178 offset:3072
	s_mov_b32 m0, s15
	v_lshl_add_u64 v[224:225], s[40:41], 0, v[134:135]
	ds_read_b128 v[182:185], v152 offset:32768
	ds_read_b128 v[186:189], v152 offset:33792
	ds_read_b128 v[190:193], v152 offset:34816
	ds_read_b128 v[194:197], v152 offset:35840
	ds_read_b128 v[198:201], v152 offset:36864
	ds_read_b128 v[202:205], v152 offset:37888
	ds_read_b128 v[206:209], v152 offset:38912
	ds_read_b128 v[212:215], v152 offset:39936
	global_load_lds_dwordx4 v[224:225], off
	v_lshl_add_u64 v[224:225], s[40:41], 0, v[130:131]
	s_mov_b32 m0, s27
	s_nop 0
	global_load_lds_dwordx4 v[224:225], off
	s_waitcnt vmcnt(8)
	s_waitcnt lgkmcnt(0)
	s_barrier
	s_setprio 1
	s_waitcnt lgkmcnt(0)
	v_mfma_f32_16x16x32_bf16 v[124:127], v[144:147], v[182:185], v[124:127]
	v_mfma_f32_16x16x32_bf16 v[120:123], v[158:161], v[182:185], v[120:123]
	v_mfma_f32_16x16x32_bf16 v[108:111], v[144:147], v[190:193], v[108:111]
	v_mfma_f32_16x16x32_bf16 v[104:107], v[158:161], v[190:193], v[104:107]
	s_setprio 0
	s_setprio 1
	v_mfma_f32_16x16x32_bf16 v[92:95], v[144:147], v[198:201], v[92:95]
	v_mfma_f32_16x16x32_bf16 v[88:91], v[158:161], v[198:201], v[88:91]
	v_mfma_f32_16x16x32_bf16 v[76:79], v[144:147], v[206:209], v[76:79]
	v_mfma_f32_16x16x32_bf16 v[72:75], v[158:161], v[206:209], v[72:75]
	s_setprio 0
	s_setprio 1
	v_mfma_f32_16x16x32_bf16 v[124:127], v[154:157], v[186:189], v[124:127]
	v_mfma_f32_16x16x32_bf16 v[120:123], v[162:165], v[186:189], v[120:123]
	v_mfma_f32_16x16x32_bf16 v[108:111], v[154:157], v[194:197], v[108:111]
	v_mfma_f32_16x16x32_bf16 v[104:107], v[162:165], v[194:197], v[104:107]
	s_setprio 0
	s_setprio 1
	v_mfma_f32_16x16x32_bf16 v[92:95], v[154:157], v[202:205], v[92:95]
	v_mfma_f32_16x16x32_bf16 v[88:91], v[162:165], v[202:205], v[88:91]
	v_mfma_f32_16x16x32_bf16 v[76:79], v[154:157], v[212:215], v[76:79]
	v_mfma_f32_16x16x32_bf16 v[72:75], v[162:165], v[212:215], v[72:75]
	s_setprio 0
	s_setprio 1
	v_mfma_f32_16x16x32_bf16 v[116:119], v[166:169], v[182:185], v[116:119]
	v_mfma_f32_16x16x32_bf16 v[112:115], v[174:177], v[182:185], v[112:115]
	v_mfma_f32_16x16x32_bf16 v[100:103], v[166:169], v[190:193], v[100:103]
	v_mfma_f32_16x16x32_bf16 v[96:99], v[174:177], v[190:193], v[96:99]
	s_setprio 0
	s_setprio 1
	v_mfma_f32_16x16x32_bf16 v[84:87], v[166:169], v[198:201], v[84:87]
	v_mfma_f32_16x16x32_bf16 v[80:83], v[174:177], v[198:201], v[80:83]
	v_mfma_f32_16x16x32_bf16 v[68:71], v[166:169], v[206:209], v[68:71]
	v_mfma_f32_16x16x32_bf16 v[64:67], v[174:177], v[206:209], v[64:67]
	s_setprio 0
	s_setprio 1
	v_mfma_f32_16x16x32_bf16 v[116:119], v[170:173], v[186:189], v[116:119]
	v_mfma_f32_16x16x32_bf16 v[112:115], v[178:181], v[186:189], v[112:115]
	v_mfma_f32_16x16x32_bf16 v[100:103], v[170:173], v[194:197], v[100:103]
	v_mfma_f32_16x16x32_bf16 v[96:99], v[178:181], v[194:197], v[96:99]
	s_setprio 0
	s_setprio 1
	v_mfma_f32_16x16x32_bf16 v[84:87], v[170:173], v[202:205], v[84:87]
	v_mfma_f32_16x16x32_bf16 v[80:83], v[178:181], v[202:205], v[80:83]
	v_mfma_f32_16x16x32_bf16 v[68:71], v[170:173], v[212:215], v[68:71]
	v_mfma_f32_16x16x32_bf16 v[64:67], v[178:181], v[212:215], v[64:67]
	s_setprio 0
	s_barrier
	s_mov_b32 m0, s58
	v_lshl_add_u64 v[216:217], v[216:217], 0, s[2:3]
	ds_read_b128 v[182:185], v152 offset:49152
	ds_read_b128 v[186:189], v152 offset:50176
	ds_read_b128 v[190:193], v152 offset:51200
	ds_read_b128 v[194:197], v152 offset:52224
	ds_read_b128 v[198:201], v152 offset:53248
	ds_read_b128 v[202:205], v152 offset:54272
	ds_read_b128 v[206:209], v152 offset:55296
	ds_read_b128 v[212:215], v152 offset:56320
	global_load_lds_dwordx4 v[216:217], off
	v_lshl_add_u64 v[216:217], v[218:219], 0, s[2:3]
	s_mov_b32 m0, s56
	s_nop 0
	global_load_lds_dwordx4 v[216:217], off
	v_lshl_add_u64 v[216:217], s[38:39], 0, v[132:133]
	s_mov_b32 m0, s57
	s_nop 0
	global_load_lds_dwordx4 v[216:217], off
	v_lshl_add_u64 v[216:217], s[38:39], 0, v[128:129]
	s_mov_b32 m0, s55
	s_nop 0
	global_load_lds_dwordx4 v[216:217], off
	v_lshl_add_u64 v[216:217], v[220:221], 0, s[2:3]
	s_mov_b32 m0, s29
	s_nop 0
	global_load_lds_dwordx4 v[216:217], off
	v_lshl_add_u64 v[216:217], v[222:223], 0, s[2:3]
	s_mov_b32 m0, s33
	s_nop 0
	global_load_lds_dwordx4 v[216:217], off
	s_waitcnt vmcnt(8)
	s_waitcnt lgkmcnt(0)
	s_barrier
	s_setprio 1
	s_waitcnt lgkmcnt(0)
	v_mfma_f32_16x16x32_bf16 v[60:63], v[144:147], v[182:185], v[60:63]
	v_mfma_f32_16x16x32_bf16 v[56:59], v[158:161], v[182:185], v[56:59]
	v_mfma_f32_16x16x32_bf16 v[44:47], v[144:147], v[190:193], v[44:47]
	v_mfma_f32_16x16x32_bf16 v[40:43], v[158:161], v[190:193], v[40:43]
	s_setprio 0
	s_setprio 1
	v_mfma_f32_16x16x32_bf16 v[28:31], v[144:147], v[198:201], v[28:31]
	v_mfma_f32_16x16x32_bf16 v[24:27], v[158:161], v[198:201], v[24:27]
	v_mfma_f32_16x16x32_bf16 v[12:15], v[144:147], v[206:209], v[12:15]
	v_mfma_f32_16x16x32_bf16 v[8:11], v[158:161], v[206:209], v[8:11]
	s_setprio 0
	s_setprio 1
	v_mfma_f32_16x16x32_bf16 v[60:63], v[154:157], v[186:189], v[60:63]
	v_mfma_f32_16x16x32_bf16 v[56:59], v[162:165], v[186:189], v[56:59]
	v_mfma_f32_16x16x32_bf16 v[44:47], v[154:157], v[194:197], v[44:47]
	v_mfma_f32_16x16x32_bf16 v[40:43], v[162:165], v[194:197], v[40:43]
	s_setprio 0
	s_setprio 1
	v_mfma_f32_16x16x32_bf16 v[28:31], v[154:157], v[202:205], v[28:31]
	v_mfma_f32_16x16x32_bf16 v[24:27], v[162:165], v[202:205], v[24:27]
	v_mfma_f32_16x16x32_bf16 v[12:15], v[154:157], v[212:215], v[12:15]
	v_mfma_f32_16x16x32_bf16 v[8:11], v[162:165], v[212:215], v[8:11]
	s_setprio 0
	s_setprio 1
	v_mfma_f32_16x16x32_bf16 v[52:55], v[166:169], v[182:185], v[52:55]
	v_mfma_f32_16x16x32_bf16 v[48:51], v[174:177], v[182:185], v[48:51]
	v_mfma_f32_16x16x32_bf16 v[36:39], v[166:169], v[190:193], v[36:39]
	v_mfma_f32_16x16x32_bf16 v[32:35], v[174:177], v[190:193], v[32:35]
	s_setprio 0
	s_setprio 1
	v_mfma_f32_16x16x32_bf16 v[20:23], v[166:169], v[198:201], v[20:23]
	v_mfma_f32_16x16x32_bf16 v[16:19], v[174:177], v[198:201], v[16:19]
	v_mfma_f32_16x16x32_bf16 v[4:7], v[166:169], v[206:209], v[4:7]
	v_mfma_f32_16x16x32_bf16 v[0:3], v[174:177], v[206:209], v[0:3]
	s_setprio 0
	s_setprio 1
	v_mfma_f32_16x16x32_bf16 v[52:55], v[170:173], v[186:189], v[52:55]
	v_mfma_f32_16x16x32_bf16 v[48:51], v[178:181], v[186:189], v[48:51]
	v_mfma_f32_16x16x32_bf16 v[36:39], v[170:173], v[194:197], v[36:39]
	v_mfma_f32_16x16x32_bf16 v[32:35], v[178:181], v[194:197], v[32:35]
	s_setprio 0
	s_setprio 1
	v_mfma_f32_16x16x32_bf16 v[20:23], v[170:173], v[202:205], v[20:23]
	v_mfma_f32_16x16x32_bf16 v[16:19], v[178:181], v[202:205], v[16:19]
	v_mfma_f32_16x16x32_bf16 v[4:7], v[170:173], v[212:215], v[4:7]
	v_mfma_f32_16x16x32_bf16 v[0:3], v[178:181], v[212:215], v[0:3]
	s_setprio 0
	s_barrier
	s_andn2_b64 vcc, exec, s[36:37]
	s_mov_b64 s[38:39], -1
	s_mov_b64 s[36:37], 0
	s_mov_b64 s[40:41], 0x100
	s_cbranch_vccz .LBB0_894
	s_and_b64 vcc, exec, s[6:7]
	s_cbranch_vccz .LBB0_897
	s_barrier

.LBB0_1155:
	v_add_u32_e32 v1, s46, v193
	ds_read_b128 v[72:75], v1
	ds_read_b128 v[76:79], v1 offset:1024
	ds_read_b128 v[84:87], v1 offset:2048
	ds_read_b128 v[188:191], v1 offset:3072
	v_add_u32_e32 v1, s47, v193
	s_add_u32 s34, s28, s30
	ds_read_b128 v[198:201], v1
	ds_read_b128 v[202:205], v1 offset:1024
	ds_read_b128 v[206:209], v1 offset:2048
	ds_read_b128 v[210:213], v1 offset:3072
	s_addc_u32 s35, s29, s31
	s_add_u32 s34, s34, 0x100
	s_addc_u32 s35, s35, 0
	s_add_u32 s53, s50, s30
	s_addc_u32 s54, s51, s31
	s_cmpk_eq_i32 s30, 0x700
	s_cselect_b32 s37, s21, s35
	s_cselect_b32 s36, s27, s34
	s_cselect_b32 s35, s19, s54
	s_cselect_b32 s34, s49, s53
	v_lshl_add_u64 v[2:3], v[112:113], 0, s[30:31]
	s_add_i32 m0, s38, 0xc000
	ds_read_b128 v[216:219], v197
	ds_read_b128 v[220:223], v197 offset:1024
	ds_read_b128 v[224:227], v197 offset:2048
	ds_read_b128 v[228:231], v197 offset:3072
	ds_read_b128 v[232:235], v197 offset:4096
	ds_read_b128 v[236:239], v197 offset:5120
	ds_read_b128 v[240:243], v197 offset:6144
	ds_read_b128 v[244:247], v197 offset:7168
	global_load_lds_dwordx4 v[2:3], off
	v_lshl_add_u64 v[2:3], v[114:115], 0, s[30:31]
	s_add_i32 m0, s38, 0xe000
	s_nop 0
	global_load_lds_dwordx4 v[2:3], off
	s_waitcnt vmcnt(8)
	s_waitcnt lgkmcnt(0)
	s_barrier
	s_setprio 1
	s_waitcnt lgkmcnt(0)
	v_mfma_f32_16x16x32_bf16 v[156:159], v[72:75], v[216:219], v[156:159]
	v_mfma_f32_16x16x32_bf16 v[160:163], v[84:87], v[216:219], v[160:163]
	v_mfma_f32_16x16x32_bf16 v[144:147], v[72:75], v[224:227], v[144:147]
	v_mfma_f32_16x16x32_bf16 v[140:143], v[84:87], v[224:227], v[140:143]
	s_setprio 0
	s_setprio 1
	v_mfma_f32_16x16x32_bf16 v[128:131], v[72:75], v[232:235], v[128:131]
	v_mfma_f32_16x16x32_bf16 v[124:127], v[84:87], v[232:235], v[124:127]
	v_mfma_f32_16x16x32_bf16 v[96:99], v[72:75], v[240:243], v[96:99]
	v_mfma_f32_16x16x32_bf16 v[92:95], v[84:87], v[240:243], v[92:95]
	s_setprio 0
	s_setprio 1
	v_mfma_f32_16x16x32_bf16 v[156:159], v[76:79], v[220:223], v[156:159]
	v_mfma_f32_16x16x32_bf16 v[160:163], v[188:191], v[220:223], v[160:163]
	v_mfma_f32_16x16x32_bf16 v[144:147], v[76:79], v[228:231], v[144:147]
	v_mfma_f32_16x16x32_bf16 v[140:143], v[188:191], v[228:231], v[140:143]
	s_setprio 0
	s_setprio 1
	v_mfma_f32_16x16x32_bf16 v[128:131], v[76:79], v[236:239], v[128:131]
	v_mfma_f32_16x16x32_bf16 v[124:127], v[188:191], v[236:239], v[124:127]
	v_mfma_f32_16x16x32_bf16 v[96:99], v[76:79], v[244:247], v[96:99]
	v_mfma_f32_16x16x32_bf16 v[92:95], v[188:191], v[244:247], v[92:95]
	s_setprio 0
	s_setprio 1
	v_mfma_f32_16x16x32_bf16 v[152:155], v[198:201], v[216:219], v[152:155]
	v_mfma_f32_16x16x32_bf16 v[148:151], v[206:209], v[216:219], v[148:151]
	v_mfma_f32_16x16x32_bf16 v[136:139], v[198:201], v[224:227], v[136:139]
	v_mfma_f32_16x16x32_bf16 v[132:135], v[206:209], v[224:227], v[132:135]
	s_setprio 0
	s_setprio 1
	v_mfma_f32_16x16x32_bf16 v[120:123], v[198:201], v[232:235], v[120:123]
	v_mfma_f32_16x16x32_bf16 v[116:119], v[206:209], v[232:235], v[116:119]
	v_mfma_f32_16x16x32_bf16 v[80:83], v[198:201], v[240:243], v[80:83]
	v_mfma_f32_16x16x32_bf16 v[68:71], v[206:209], v[240:243], v[68:71]
	s_setprio 0
	s_setprio 1
	v_mfma_f32_16x16x32_bf16 v[152:155], v[202:205], v[220:223], v[152:155]
	v_mfma_f32_16x16x32_bf16 v[148:151], v[210:213], v[220:223], v[148:151]
	v_mfma_f32_16x16x32_bf16 v[136:139], v[202:205], v[228:231], v[136:139]
	v_mfma_f32_16x16x32_bf16 v[132:135], v[210:213], v[228:231], v[132:135]
	s_setprio 0
	s_setprio 1
	v_mfma_f32_16x16x32_bf16 v[120:123], v[202:205], v[236:239], v[120:123]
	v_mfma_f32_16x16x32_bf16 v[116:119], v[210:213], v[236:239], v[116:119]
	v_mfma_f32_16x16x32_bf16 v[80:83], v[202:205], v[244:247], v[80:83]
	v_mfma_f32_16x16x32_bf16 v[68:71], v[210:213], v[244:247], v[68:71]
	s_setprio 0
	s_barrier
	s_add_i32 s53, s46, s33
	v_lshl_add_u64 v[248:249], s[34:35], 0, v[166:167]
	s_mov_b32 m0, s53
	ds_read_b128 v[216:219], v197 offset:16384
	ds_read_b128 v[220:223], v197 offset:17408
	ds_read_b128 v[224:227], v197 offset:18432
	ds_read_b128 v[228:231], v197 offset:19456
	ds_read_b128 v[232:235], v197 offset:20480
	ds_read_b128 v[236:239], v197 offset:21504
	ds_read_b128 v[240:243], v197 offset:22528
	ds_read_b128 v[244:247], v197 offset:23552
	global_load_lds_dwordx4 v[248:249], off
	s_add_i32 m0, s53, 0x2000
	s_add_u32 s54, s34, 0x40000
	v_lshl_add_u64 v[250:251], s[34:35], 0, v[170:171]
	s_addc_u32 s55, s35, 0
	s_add_i32 s53, s47, s33
	global_load_lds_dwordx4 v[250:251], off
	v_lshl_add_u64 v[2:3], s[54:55], 0, v[166:167]
	s_mov_b32 m0, s53
	v_lshl_add_u64 v[252:253], s[36:37], 0, v[164:165]
	global_load_lds_dwordx4 v[2:3], off
	v_lshl_add_u64 v[2:3], s[54:55], 0, v[170:171]
	s_add_i32 m0, s53, 0x2000
	v_lshl_add_u64 v[176:177], s[36:37], 0, v[168:169]
	global_load_lds_dwordx4 v[2:3], off
	s_mov_b32 m0, s38
	s_nop 0
	global_load_lds_dwordx4 v[252:253], off
	s_mov_b32 m0, s39
	s_nop 0
	global_load_lds_dwordx4 v[176:177], off
	s_waitcnt vmcnt(8)
	s_waitcnt lgkmcnt(0)
	s_barrier
	s_setprio 1
	s_waitcnt lgkmcnt(0)
	v_mfma_f32_16x16x32_bf16 v[64:67], v[72:75], v[216:219], v[64:67]
	v_mfma_f32_16x16x32_bf16 v[60:63], v[84:87], v[216:219], v[60:63]
	v_mfma_f32_16x16x32_bf16 v[48:51], v[72:75], v[224:227], v[48:51]
	v_mfma_f32_16x16x32_bf16 v[44:47], v[84:87], v[224:227], v[44:47]
	s_setprio 0
	s_setprio 1
	v_mfma_f32_16x16x32_bf16 v[32:35], v[72:75], v[232:235], v[32:35]
	v_mfma_f32_16x16x32_bf16 v[28:31], v[84:87], v[232:235], v[28:31]
	v_mfma_f32_16x16x32_bf16 v[16:19], v[72:75], v[240:243], v[16:19]
	v_mfma_f32_16x16x32_bf16 v[12:15], v[84:87], v[240:243], v[12:15]
	s_setprio 0
	s_setprio 1
	v_mfma_f32_16x16x32_bf16 v[64:67], v[76:79], v[220:223], v[64:67]
	v_mfma_f32_16x16x32_bf16 v[60:63], v[188:191], v[220:223], v[60:63]
	v_mfma_f32_16x16x32_bf16 v[48:51], v[76:79], v[228:231], v[48:51]
	v_mfma_f32_16x16x32_bf16 v[44:47], v[188:191], v[228:231], v[44:47]
	s_setprio 0
	s_setprio 1
	v_mfma_f32_16x16x32_bf16 v[32:35], v[76:79], v[236:239], v[32:35]
	v_mfma_f32_16x16x32_bf16 v[28:31], v[188:191], v[236:239], v[28:31]
	v_mfma_f32_16x16x32_bf16 v[16:19], v[76:79], v[244:247], v[16:19]
	v_mfma_f32_16x16x32_bf16 v[12:15], v[188:191], v[244:247], v[12:15]
	s_setprio 0
	s_setprio 1
	v_mfma_f32_16x16x32_bf16 v[56:59], v[198:201], v[216:219], v[56:59]
	v_mfma_f32_16x16x32_bf16 v[52:55], v[206:209], v[216:219], v[52:55]
	v_mfma_f32_16x16x32_bf16 v[40:43], v[198:201], v[224:227], v[40:43]
	v_mfma_f32_16x16x32_bf16 v[36:39], v[206:209], v[224:227], v[36:39]
	s_setprio 0
	s_setprio 1
	v_mfma_f32_16x16x32_bf16 v[24:27], v[198:201], v[232:235], v[24:27]
	v_mfma_f32_16x16x32_bf16 v[20:23], v[206:209], v[232:235], v[20:23]
	v_mfma_f32_16x16x32_bf16 v[8:11], v[198:201], v[240:243], v[8:11]
	v_mfma_f32_16x16x32_bf16 v[2:5], v[206:209], v[240:243], v[4:7]
	s_setprio 0
	s_setprio 1
	v_mfma_f32_16x16x32_bf16 v[56:59], v[202:205], v[220:223], v[56:59]
	v_mfma_f32_16x16x32_bf16 v[52:55], v[210:213], v[220:223], v[52:55]
	v_mfma_f32_16x16x32_bf16 v[40:43], v[202:205], v[228:231], v[40:43]
	v_mfma_f32_16x16x32_bf16 v[36:39], v[210:213], v[228:231], v[36:39]
	s_setprio 0
	s_setprio 1
	v_mfma_f32_16x16x32_bf16 v[24:27], v[202:205], v[236:239], v[24:27]
	v_mfma_f32_16x16x32_bf16 v[20:23], v[210:213], v[236:239], v[20:23]
	v_mfma_f32_16x16x32_bf16 v[8:11], v[202:205], v[244:247], v[8:11]
	v_mfma_f32_16x16x32_bf16 v[2:5], v[210:213], v[244:247], v[2:5]
	s_setprio 0
	s_barrier
	s_add_i32 s53, 0, 0x18000
	v_add_u32_e32 v1, s53, v193
	s_add_i32 s54, 0, 0x1c000
	ds_read_b128 v[72:75], v1
	ds_read_b128 v[76:79], v1 offset:1024
	ds_read_b128 v[84:87], v1 offset:2048
	ds_read_b128 v[188:191], v1 offset:3072
	v_add_u32_e32 v1, s54, v193
	ds_read_b128 v[198:201], v1
	ds_read_b128 v[202:205], v1 offset:1024
	ds_read_b128 v[206:209], v1 offset:2048
	ds_read_b128 v[210:213], v1 offset:3072
	s_add_u32 s36, s36, 0x40000
	s_addc_u32 s37, s37, 0
	s_mov_b32 m0, s40
	v_lshl_add_u64 v[6:7], s[36:37], 0, v[164:165]
	ds_read_b128 v[216:219], v197 offset:32768
	ds_read_b128 v[220:223], v197 offset:33792
	ds_read_b128 v[224:227], v197 offset:34816
	ds_read_b128 v[228:231], v197 offset:35840
	ds_read_b128 v[232:235], v197 offset:36864
	ds_read_b128 v[236:239], v197 offset:37888
	ds_read_b128 v[240:243], v197 offset:38912
	ds_read_b128 v[244:247], v197 offset:39936
	global_load_lds_dwordx4 v[6:7], off
	v_lshl_add_u64 v[6:7], s[36:37], 0, v[168:169]
	s_mov_b32 m0, s41
	s_nop 0
	global_load_lds_dwordx4 v[6:7], off
	s_waitcnt vmcnt(8)
	s_waitcnt lgkmcnt(0)
	s_barrier
	s_setprio 1
	s_waitcnt lgkmcnt(0)
	v_mfma_f32_16x16x32_bf16 v[156:159], v[72:75], v[216:219], v[156:159]
	v_mfma_f32_16x16x32_bf16 v[160:163], v[84:87], v[216:219], v[160:163]
	v_mfma_f32_16x16x32_bf16 v[144:147], v[72:75], v[224:227], v[144:147]
	v_mfma_f32_16x16x32_bf16 v[140:143], v[84:87], v[224:227], v[140:143]
	s_setprio 0
	s_setprio 1
	v_mfma_f32_16x16x32_bf16 v[128:131], v[72:75], v[232:235], v[128:131]
	v_mfma_f32_16x16x32_bf16 v[124:127], v[84:87], v[232:235], v[124:127]
	v_mfma_f32_16x16x32_bf16 v[96:99], v[72:75], v[240:243], v[96:99]
	v_mfma_f32_16x16x32_bf16 v[92:95], v[84:87], v[240:243], v[92:95]
	s_setprio 0
	s_setprio 1
	v_mfma_f32_16x16x32_bf16 v[156:159], v[76:79], v[220:223], v[156:159]
	v_mfma_f32_16x16x32_bf16 v[160:163], v[188:191], v[220:223], v[160:163]
	v_mfma_f32_16x16x32_bf16 v[144:147], v[76:79], v[228:231], v[144:147]
	v_mfma_f32_16x16x32_bf16 v[140:143], v[188:191], v[228:231], v[140:143]
	s_setprio 0
	s_setprio 1
	v_mfma_f32_16x16x32_bf16 v[128:131], v[76:79], v[236:239], v[128:131]
	v_mfma_f32_16x16x32_bf16 v[124:127], v[188:191], v[236:239], v[124:127]
	v_mfma_f32_16x16x32_bf16 v[96:99], v[76:79], v[244:247], v[96:99]
	v_mfma_f32_16x16x32_bf16 v[92:95], v[188:191], v[244:247], v[92:95]
	s_setprio 0
	s_setprio 1
	v_mfma_f32_16x16x32_bf16 v[152:155], v[198:201], v[216:219], v[152:155]
	v_mfma_f32_16x16x32_bf16 v[148:151], v[206:209], v[216:219], v[148:151]
	v_mfma_f32_16x16x32_bf16 v[136:139], v[198:201], v[224:227], v[136:139]
	v_mfma_f32_16x16x32_bf16 v[132:135], v[206:209], v[224:227], v[132:135]
	s_setprio 0
	s_setprio 1
	v_mfma_f32_16x16x32_bf16 v[120:123], v[198:201], v[232:235], v[120:123]
	v_mfma_f32_16x16x32_bf16 v[116:119], v[206:209], v[232:235], v[116:119]
	v_mfma_f32_16x16x32_bf16 v[80:83], v[198:201], v[240:243], v[80:83]
	v_mfma_f32_16x16x32_bf16 v[68:71], v[206:209], v[240:243], v[68:71]
	s_setprio 0
	s_setprio 1
	v_mfma_f32_16x16x32_bf16 v[152:155], v[202:205], v[220:223], v[152:155]
	v_mfma_f32_16x16x32_bf16 v[148:151], v[210:213], v[220:223], v[148:151]
	v_mfma_f32_16x16x32_bf16 v[136:139], v[202:205], v[228:231], v[136:139]
	v_mfma_f32_16x16x32_bf16 v[132:135], v[210:213], v[228:231], v[132:135]
	s_setprio 0
	s_setprio 1
	v_mfma_f32_16x16x32_bf16 v[120:123], v[202:205], v[236:239], v[120:123]
	v_mfma_f32_16x16x32_bf16 v[116:119], v[210:213], v[236:239], v[116:119]
	v_mfma_f32_16x16x32_bf16 v[80:83], v[202:205], v[244:247], v[80:83]
	v_mfma_f32_16x16x32_bf16 v[68:71], v[210:213], v[244:247], v[68:71]
	s_setprio 0
	s_barrier
	s_add_i32 s36, s53, s33
	v_lshl_add_u64 v[6:7], v[248:249], 0, s[10:11]
	s_mov_b32 m0, s36
	ds_read_b128 v[216:219], v197 offset:49152
	ds_read_b128 v[220:223], v197 offset:50176
	ds_read_b128 v[224:227], v197 offset:51200
	ds_read_b128 v[228:231], v197 offset:52224
	ds_read_b128 v[232:235], v197 offset:53248
	ds_read_b128 v[236:239], v197 offset:54272
	ds_read_b128 v[240:243], v197 offset:55296
	ds_read_b128 v[244:247], v197 offset:56320
	global_load_lds_dwordx4 v[6:7], off
	s_add_i32 m0, s36, 0x2000
	s_add_u32 s34, s34, 0x40080
	v_lshl_add_u64 v[6:7], v[250:251], 0, s[10:11]
	s_addc_u32 s35, s35, 0
	s_add_i32 s36, s54, s33
	global_load_lds_dwordx4 v[6:7], off
	v_lshl_add_u64 v[6:7], s[34:35], 0, v[166:167]
	s_mov_b32 m0, s36
	s_nop 0
	global_load_lds_dwordx4 v[6:7], off
	v_lshl_add_u64 v[6:7], s[34:35], 0, v[170:171]
	s_add_i32 m0, s36, 0x2000
	s_nop 0
	global_load_lds_dwordx4 v[6:7], off
	v_lshl_add_u64 v[6:7], v[252:253], 0, s[10:11]
	s_mov_b32 m0, s43
	s_nop 0
	global_load_lds_dwordx4 v[6:7], off
	v_lshl_add_u64 v[6:7], v[176:177], 0, s[10:11]
	s_mov_b32 m0, s44
	s_nop 0
	global_load_lds_dwordx4 v[6:7], off
	s_waitcnt vmcnt(8)
	s_waitcnt lgkmcnt(0)
	s_barrier
	s_setprio 1
	s_waitcnt lgkmcnt(0)
	v_mfma_f32_16x16x32_bf16 v[64:67], v[72:75], v[216:219], v[64:67]
	v_mfma_f32_16x16x32_bf16 v[60:63], v[84:87], v[216:219], v[60:63]
	v_mfma_f32_16x16x32_bf16 v[48:51], v[72:75], v[224:227], v[48:51]
	v_mfma_f32_16x16x32_bf16 v[44:47], v[84:87], v[224:227], v[44:47]
	s_setprio 0
	s_setprio 1
	v_mfma_f32_16x16x32_bf16 v[32:35], v[72:75], v[232:235], v[32:35]
	v_mfma_f32_16x16x32_bf16 v[28:31], v[84:87], v[232:235], v[28:31]
	v_mfma_f32_16x16x32_bf16 v[16:19], v[72:75], v[240:243], v[16:19]
	v_mfma_f32_16x16x32_bf16 v[12:15], v[84:87], v[240:243], v[12:15]
	s_setprio 0
	s_setprio 1
	v_mfma_f32_16x16x32_bf16 v[64:67], v[76:79], v[220:223], v[64:67]
	v_mfma_f32_16x16x32_bf16 v[60:63], v[188:191], v[220:223], v[60:63]
	v_mfma_f32_16x16x32_bf16 v[48:51], v[76:79], v[228:231], v[48:51]
	v_mfma_f32_16x16x32_bf16 v[44:47], v[188:191], v[228:231], v[44:47]
	s_setprio 0
	s_setprio 1
	v_mfma_f32_16x16x32_bf16 v[32:35], v[76:79], v[236:239], v[32:35]
	v_mfma_f32_16x16x32_bf16 v[28:31], v[188:191], v[236:239], v[28:31]
	v_mfma_f32_16x16x32_bf16 v[16:19], v[76:79], v[244:247], v[16:19]
	v_mfma_f32_16x16x32_bf16 v[12:15], v[188:191], v[244:247], v[12:15]
	s_setprio 0
	s_setprio 1
	v_mfma_f32_16x16x32_bf16 v[56:59], v[198:201], v[216:219], v[56:59]
	v_mfma_f32_16x16x32_bf16 v[52:55], v[206:209], v[216:219], v[52:55]
	v_mfma_f32_16x16x32_bf16 v[40:43], v[198:201], v[224:227], v[40:43]
	v_mfma_f32_16x16x32_bf16 v[36:39], v[206:209], v[224:227], v[36:39]
	s_setprio 0
	s_setprio 1
	v_mfma_f32_16x16x32_bf16 v[24:27], v[198:201], v[232:235], v[24:27]
	v_mfma_f32_16x16x32_bf16 v[20:23], v[206:209], v[232:235], v[20:23]
	v_mfma_f32_16x16x32_bf16 v[6:9], v[198:201], v[240:243], v[8:11]
	v_mfma_f32_16x16x32_bf16 v[2:5], v[206:209], v[240:243], v[2:5]
	s_setprio 0
	s_setprio 1
	v_mfma_f32_16x16x32_bf16 v[56:59], v[202:205], v[220:223], v[56:59]
	v_mfma_f32_16x16x32_bf16 v[52:55], v[210:213], v[220:223], v[52:55]
	v_mfma_f32_16x16x32_bf16 v[40:43], v[202:205], v[228:231], v[40:43]
	v_mfma_f32_16x16x32_bf16 v[36:39], v[210:213], v[228:231], v[36:39]
	s_setprio 0
	s_setprio 1
	v_mfma_f32_16x16x32_bf16 v[24:27], v[202:205], v[236:239], v[24:27]
	v_mfma_f32_16x16x32_bf16 v[20:23], v[210:213], v[236:239], v[20:23]
	v_mfma_f32_16x16x32_bf16 v[8:11], v[202:205], v[244:247], v[6:9]
	v_mfma_f32_16x16x32_bf16 v[4:7], v[210:213], v[244:247], v[2:5]
	s_setprio 0
	s_barrier
	s_add_i32 s52, s52, 2
	s_add_u32 s30, s30, 0x100
	s_addc_u32 s31, s31, 0
	s_cmp_gt_u32 s52, 13
	s_cbranch_scc1 .LBB0_1158

.LBB0_1243:
	ds_read_b128 v[128:131], v183
	ds_read_b128 v[132:135], v183 offset:1024
	ds_read_b128 v[136:139], v183 offset:2048
	ds_read_b128 v[140:143], v183 offset:3072
	ds_read_b128 v[144:147], v184
	ds_read_b128 v[164:167], v184 offset:1024
	ds_read_b128 v[168:171], v184 offset:2048
	ds_read_b128 v[172:175], v184 offset:3072
	s_add_u32 s20, s18, 0xfffc0080
	s_addc_u32 s21, s19, -1
	s_cmp_eq_u32 s44, 12
	s_cselect_b32 s23, s13, s21
	s_cselect_b32 s22, s40, s20
	s_cselect_b32 s21, s11, s43
	s_cselect_b32 s20, s41, s42
	v_lshl_add_u64 v[212:213], s[18:19], 0, v[156:157]
	s_add_i32 m0, s25, 0xc000
	ds_read_b128 v[176:179], v185
	ds_read_b128 v[188:191], v185 offset:1024
	ds_read_b128 v[192:195], v185 offset:2048
	ds_read_b128 v[196:199], v185 offset:3072
	ds_read_b128 v[200:203], v185 offset:4096
	ds_read_b128 v[204:207], v185 offset:5120
	ds_read_b128 v[208:211], v185 offset:6144
	ds_read_b128 v[216:219], v185 offset:7168
	global_load_lds_dwordx4 v[212:213], off
	v_lshl_add_u64 v[212:213], s[18:19], 0, v[158:159]
	s_add_i32 m0, s25, 0xe000
	s_nop 0
	global_load_lds_dwordx4 v[212:213], off
	s_waitcnt vmcnt(8)
	s_waitcnt lgkmcnt(0)
	s_barrier
	s_setprio 1
	s_waitcnt lgkmcnt(0)
	v_mfma_f32_16x16x32_bf16 v[124:127], v[128:131], v[176:179], v[124:127]
	v_mfma_f32_16x16x32_bf16 v[120:123], v[136:139], v[176:179], v[120:123]
	v_mfma_f32_16x16x32_bf16 v[116:119], v[128:131], v[192:195], v[116:119]
	v_mfma_f32_16x16x32_bf16 v[112:115], v[136:139], v[192:195], v[112:115]
	s_setprio 0
	s_setprio 1
	v_mfma_f32_16x16x32_bf16 v[108:111], v[128:131], v[200:203], v[108:111]
	v_mfma_f32_16x16x32_bf16 v[100:103], v[136:139], v[200:203], v[100:103]
	v_mfma_f32_16x16x32_bf16 v[88:91], v[128:131], v[208:211], v[88:91]
	v_mfma_f32_16x16x32_bf16 v[80:83], v[136:139], v[208:211], v[80:83]
	s_setprio 0
	s_setprio 1
	v_mfma_f32_16x16x32_bf16 v[124:127], v[132:135], v[188:191], v[124:127]
	v_mfma_f32_16x16x32_bf16 v[120:123], v[140:143], v[188:191], v[120:123]
	v_mfma_f32_16x16x32_bf16 v[116:119], v[132:135], v[196:199], v[116:119]
	v_mfma_f32_16x16x32_bf16 v[112:115], v[140:143], v[196:199], v[112:115]
	s_setprio 0
	s_setprio 1
	v_mfma_f32_16x16x32_bf16 v[108:111], v[132:135], v[204:207], v[108:111]
	v_mfma_f32_16x16x32_bf16 v[100:103], v[140:143], v[204:207], v[100:103]
	v_mfma_f32_16x16x32_bf16 v[88:91], v[132:135], v[216:219], v[88:91]
	v_mfma_f32_16x16x32_bf16 v[80:83], v[140:143], v[216:219], v[80:83]
	s_setprio 0
	s_setprio 1
	v_mfma_f32_16x16x32_bf16 v[104:107], v[144:147], v[176:179], v[104:107]
	v_mfma_f32_16x16x32_bf16 v[96:99], v[168:171], v[176:179], v[96:99]
	v_mfma_f32_16x16x32_bf16 v[92:95], v[144:147], v[192:195], v[92:95]
	v_mfma_f32_16x16x32_bf16 v[84:87], v[168:171], v[192:195], v[84:87]
	s_setprio 0
	s_setprio 1
	v_mfma_f32_16x16x32_bf16 v[76:79], v[144:147], v[200:203], v[76:79]
	v_mfma_f32_16x16x32_bf16 v[72:75], v[168:171], v[200:203], v[72:75]
	v_mfma_f32_16x16x32_bf16 v[68:71], v[144:147], v[208:211], v[68:71]
	v_mfma_f32_16x16x32_bf16 v[64:67], v[168:171], v[208:211], v[64:67]
	s_setprio 0
	s_setprio 1
	v_mfma_f32_16x16x32_bf16 v[104:107], v[164:167], v[188:191], v[104:107]
	v_mfma_f32_16x16x32_bf16 v[96:99], v[172:175], v[188:191], v[96:99]
	v_mfma_f32_16x16x32_bf16 v[92:95], v[164:167], v[196:199], v[92:95]
	v_mfma_f32_16x16x32_bf16 v[84:87], v[172:175], v[196:199], v[84:87]
	s_setprio 0
	s_setprio 1
	v_mfma_f32_16x16x32_bf16 v[76:79], v[164:167], v[204:207], v[76:79]
	v_mfma_f32_16x16x32_bf16 v[72:75], v[172:175], v[204:207], v[72:75]
	v_mfma_f32_16x16x32_bf16 v[68:71], v[164:167], v[216:219], v[68:71]
	v_mfma_f32_16x16x32_bf16 v[64:67], v[172:175], v[216:219], v[64:67]
	s_setprio 0
	s_barrier
	s_add_i32 s45, s36, s24
	v_lshl_add_u64 v[212:213], s[20:21], 0, v[152:153]
	s_mov_b32 m0, s45
	ds_read_b128 v[176:179], v185 offset:16384
	ds_read_b128 v[188:191], v185 offset:17408
	ds_read_b128 v[192:195], v185 offset:18432
	ds_read_b128 v[196:199], v185 offset:19456
	ds_read_b128 v[200:203], v185 offset:20480
	ds_read_b128 v[204:207], v185 offset:21504
	ds_read_b128 v[208:211], v185 offset:22528
	ds_read_b128 v[216:219], v185 offset:23552
	global_load_lds_dwordx4 v[212:213], off
	s_add_i32 m0, s45, 0x2000
	s_add_u32 s46, s20, 0x40000
	v_lshl_add_u64 v[220:221], s[20:21], 0, v[148:149]
	s_addc_u32 s47, s21, 0
	s_add_i32 s45, s37, s24
	global_load_lds_dwordx4 v[220:221], off
	v_lshl_add_u64 v[222:223], s[46:47], 0, v[152:153]
	s_mov_b32 m0, s45
	v_lshl_add_u64 v[224:225], s[22:23], 0, v[150:151]
	global_load_lds_dwordx4 v[222:223], off
	v_lshl_add_u64 v[222:223], s[46:47], 0, v[148:149]
	s_add_i32 m0, s45, 0x2000
	s_nop 0
	global_load_lds_dwordx4 v[222:223], off
	v_lshl_add_u64 v[222:223], s[22:23], 0, v[154:155]
	s_mov_b32 m0, s25
	s_nop 0
	global_load_lds_dwordx4 v[222:223], off
	s_mov_b32 m0, s26
	s_nop 0
	global_load_lds_dwordx4 v[224:225], off
	s_waitcnt vmcnt(8)
	s_waitcnt lgkmcnt(0)
	s_barrier
	s_setprio 1
	s_waitcnt lgkmcnt(0)
	v_mfma_f32_16x16x32_bf16 v[60:63], v[128:131], v[176:179], v[60:63]
	v_mfma_f32_16x16x32_bf16 v[56:59], v[136:139], v[176:179], v[56:59]
	v_mfma_f32_16x16x32_bf16 v[52:55], v[128:131], v[192:195], v[52:55]
	v_mfma_f32_16x16x32_bf16 v[48:51], v[136:139], v[192:195], v[48:51]
	s_setprio 0
	s_setprio 1
	v_mfma_f32_16x16x32_bf16 v[40:43], v[128:131], v[200:203], v[40:43]
	v_mfma_f32_16x16x32_bf16 v[32:35], v[136:139], v[200:203], v[32:35]
	v_mfma_f32_16x16x32_bf16 v[20:23], v[128:131], v[208:211], v[20:23]
	v_mfma_f32_16x16x32_bf16 v[16:19], v[136:139], v[208:211], v[16:19]
	s_setprio 0
	s_setprio 1
	v_mfma_f32_16x16x32_bf16 v[60:63], v[132:135], v[188:191], v[60:63]
	v_mfma_f32_16x16x32_bf16 v[56:59], v[140:143], v[188:191], v[56:59]
	v_mfma_f32_16x16x32_bf16 v[52:55], v[132:135], v[196:199], v[52:55]
	v_mfma_f32_16x16x32_bf16 v[48:51], v[140:143], v[196:199], v[48:51]
	s_setprio 0
	s_setprio 1
	v_mfma_f32_16x16x32_bf16 v[40:43], v[132:135], v[204:207], v[40:43]
	v_mfma_f32_16x16x32_bf16 v[32:35], v[140:143], v[204:207], v[32:35]
	v_mfma_f32_16x16x32_bf16 v[20:23], v[132:135], v[216:219], v[20:23]
	v_mfma_f32_16x16x32_bf16 v[16:19], v[140:143], v[216:219], v[16:19]
	s_setprio 0
	s_setprio 1
	v_mfma_f32_16x16x32_bf16 v[44:47], v[144:147], v[176:179], v[44:47]
	v_mfma_f32_16x16x32_bf16 v[36:39], v[168:171], v[176:179], v[36:39]
	v_mfma_f32_16x16x32_bf16 v[28:31], v[144:147], v[192:195], v[28:31]
	v_mfma_f32_16x16x32_bf16 v[24:27], v[168:171], v[192:195], v[24:27]
	s_setprio 0
	s_setprio 1
	v_mfma_f32_16x16x32_bf16 v[12:15], v[144:147], v[200:203], v[12:15]
	v_mfma_f32_16x16x32_bf16 v[8:11], v[168:171], v[200:203], v[8:11]
	v_mfma_f32_16x16x32_bf16 v[4:7], v[144:147], v[208:211], v[4:7]
	v_mfma_f32_16x16x32_bf16 v[0:3], v[168:171], v[208:211], v[0:3]
	s_setprio 0
	s_setprio 1
	v_mfma_f32_16x16x32_bf16 v[44:47], v[164:167], v[188:191], v[44:47]
	v_mfma_f32_16x16x32_bf16 v[36:39], v[172:175], v[188:191], v[36:39]
	v_mfma_f32_16x16x32_bf16 v[28:31], v[164:167], v[196:199], v[28:31]
	v_mfma_f32_16x16x32_bf16 v[24:27], v[172:175], v[196:199], v[24:27]
	s_setprio 0
	s_setprio 1
	v_mfma_f32_16x16x32_bf16 v[12:15], v[164:167], v[204:207], v[12:15]
	v_mfma_f32_16x16x32_bf16 v[8:11], v[172:175], v[204:207], v[8:11]
	v_mfma_f32_16x16x32_bf16 v[4:7], v[164:167], v[216:219], v[4:7]
	v_mfma_f32_16x16x32_bf16 v[0:3], v[172:175], v[216:219], v[0:3]
	s_setprio 0
	s_barrier
	s_add_i32 s45, 0, 0x18000
	s_add_i32 s46, 0, 0x1c000
	v_add_u32_e32 v140, s45, v181
	v_add_u32_e32 v172, s46, v181
	ds_read_b128 v[128:131], v140
	ds_read_b128 v[132:135], v140 offset:1024
	ds_read_b128 v[136:139], v140 offset:2048
	ds_read_b128 v[140:143], v140 offset:3072
	ds_read_b128 v[144:147], v172
	ds_read_b128 v[164:167], v172 offset:1024
	ds_read_b128 v[168:171], v172 offset:2048
	ds_read_b128 v[172:175], v172 offset:3072
	s_add_u32 s22, s22, 0x40000
	s_addc_u32 s23, s23, 0
	s_mov_b32 m0, s27
	v_lshl_add_u64 v[226:227], s[22:23], 0, v[154:155]
	ds_read_b128 v[176:179], v185 offset:32768
	ds_read_b128 v[188:191], v185 offset:33792
	ds_read_b128 v[192:195], v185 offset:34816
	ds_read_b128 v[196:199], v185 offset:35840
	ds_read_b128 v[200:203], v185 offset:36864
	ds_read_b128 v[204:207], v185 offset:37888
	ds_read_b128 v[208:211], v185 offset:38912
	ds_read_b128 v[216:219], v185 offset:39936
	global_load_lds_dwordx4 v[226:227], off
	v_lshl_add_u64 v[226:227], s[22:23], 0, v[150:151]
	s_mov_b32 m0, s28
	s_nop 0
	global_load_lds_dwordx4 v[226:227], off
	s_waitcnt vmcnt(8)
	s_waitcnt lgkmcnt(0)
	s_barrier
	s_setprio 1
	s_waitcnt lgkmcnt(0)
	v_mfma_f32_16x16x32_bf16 v[124:127], v[128:131], v[176:179], v[124:127]
	v_mfma_f32_16x16x32_bf16 v[120:123], v[136:139], v[176:179], v[120:123]
	v_mfma_f32_16x16x32_bf16 v[116:119], v[128:131], v[192:195], v[116:119]
	v_mfma_f32_16x16x32_bf16 v[112:115], v[136:139], v[192:195], v[112:115]
	s_setprio 0
	s_setprio 1
	v_mfma_f32_16x16x32_bf16 v[108:111], v[128:131], v[200:203], v[108:111]
	v_mfma_f32_16x16x32_bf16 v[100:103], v[136:139], v[200:203], v[100:103]
	v_mfma_f32_16x16x32_bf16 v[88:91], v[128:131], v[208:211], v[88:91]
	v_mfma_f32_16x16x32_bf16 v[80:83], v[136:139], v[208:211], v[80:83]
	s_setprio 0
	s_setprio 1
	v_mfma_f32_16x16x32_bf16 v[124:127], v[132:135], v[188:191], v[124:127]
	v_mfma_f32_16x16x32_bf16 v[120:123], v[140:143], v[188:191], v[120:123]
	v_mfma_f32_16x16x32_bf16 v[116:119], v[132:135], v[196:199], v[116:119]
	v_mfma_f32_16x16x32_bf16 v[112:115], v[140:143], v[196:199], v[112:115]
	s_setprio 0
	s_setprio 1
	v_mfma_f32_16x16x32_bf16 v[108:111], v[132:135], v[204:207], v[108:111]
	v_mfma_f32_16x16x32_bf16 v[100:103], v[140:143], v[204:207], v[100:103]
	v_mfma_f32_16x16x32_bf16 v[88:91], v[132:135], v[216:219], v[88:91]
	v_mfma_f32_16x16x32_bf16 v[80:83], v[140:143], v[216:219], v[80:83]
	s_setprio 0
	s_setprio 1
	v_mfma_f32_16x16x32_bf16 v[104:107], v[144:147], v[176:179], v[104:107]
	v_mfma_f32_16x16x32_bf16 v[96:99], v[168:171], v[176:179], v[96:99]
	v_mfma_f32_16x16x32_bf16 v[92:95], v[144:147], v[192:195], v[92:95]
	v_mfma_f32_16x16x32_bf16 v[84:87], v[168:171], v[192:195], v[84:87]
	s_setprio 0
	s_setprio 1
	v_mfma_f32_16x16x32_bf16 v[76:79], v[144:147], v[200:203], v[76:79]
	v_mfma_f32_16x16x32_bf16 v[72:75], v[168:171], v[200:203], v[72:75]
	v_mfma_f32_16x16x32_bf16 v[68:71], v[144:147], v[208:211], v[68:71]
	v_mfma_f32_16x16x32_bf16 v[64:67], v[168:171], v[208:211], v[64:67]
	s_setprio 0
	s_setprio 1
	v_mfma_f32_16x16x32_bf16 v[104:107], v[164:167], v[188:191], v[104:107]
	v_mfma_f32_16x16x32_bf16 v[96:99], v[172:175], v[188:191], v[96:99]
	v_mfma_f32_16x16x32_bf16 v[92:95], v[164:167], v[196:199], v[92:95]
	v_mfma_f32_16x16x32_bf16 v[84:87], v[172:175], v[196:199], v[84:87]
	s_setprio 0
	s_setprio 1
	v_mfma_f32_16x16x32_bf16 v[76:79], v[164:167], v[204:207], v[76:79]
	v_mfma_f32_16x16x32_bf16 v[72:75], v[172:175], v[204:207], v[72:75]
	v_mfma_f32_16x16x32_bf16 v[68:71], v[164:167], v[216:219], v[68:71]
	v_mfma_f32_16x16x32_bf16 v[64:67], v[172:175], v[216:219], v[64:67]
	s_setprio 0
	s_barrier
	s_add_i32 s22, s45, s24
	v_lshl_add_u64 v[212:213], v[212:213], 0, s[6:7]
	s_mov_b32 m0, s22
	ds_read_b128 v[176:179], v185 offset:49152
	ds_read_b128 v[188:191], v185 offset:50176
	ds_read_b128 v[192:195], v185 offset:51200
	ds_read_b128 v[196:199], v185 offset:52224
	ds_read_b128 v[200:203], v185 offset:53248
	ds_read_b128 v[204:207], v185 offset:54272
	ds_read_b128 v[208:211], v185 offset:55296
	ds_read_b128 v[216:219], v185 offset:56320
	global_load_lds_dwordx4 v[212:213], off
	s_add_i32 m0, s22, 0x2000
	s_add_u32 s20, s20, 0x40080
	v_lshl_add_u64 v[212:213], v[220:221], 0, s[6:7]
	s_addc_u32 s21, s21, 0
	s_add_i32 s22, s46, s24
	global_load_lds_dwordx4 v[212:213], off
	v_lshl_add_u64 v[212:213], s[20:21], 0, v[152:153]
	s_mov_b32 m0, s22
	s_nop 0
	global_load_lds_dwordx4 v[212:213], off
	v_lshl_add_u64 v[212:213], s[20:21], 0, v[148:149]
	s_add_i32 m0, s22, 0x2000
	s_nop 0
	global_load_lds_dwordx4 v[212:213], off
	v_lshl_add_u64 v[212:213], v[222:223], 0, s[6:7]
	s_mov_b32 m0, s33
	s_nop 0
	global_load_lds_dwordx4 v[212:213], off
	v_lshl_add_u64 v[212:213], v[224:225], 0, s[6:7]
	s_mov_b32 m0, s34
	s_nop 0
	global_load_lds_dwordx4 v[212:213], off
	s_waitcnt vmcnt(8)
	s_waitcnt lgkmcnt(0)
	s_barrier
	s_setprio 1
	s_waitcnt lgkmcnt(0)
	v_mfma_f32_16x16x32_bf16 v[60:63], v[128:131], v[176:179], v[60:63]
	v_mfma_f32_16x16x32_bf16 v[56:59], v[136:139], v[176:179], v[56:59]
	v_mfma_f32_16x16x32_bf16 v[52:55], v[128:131], v[192:195], v[52:55]
	v_mfma_f32_16x16x32_bf16 v[48:51], v[136:139], v[192:195], v[48:51]
	s_setprio 0
	s_setprio 1
	v_mfma_f32_16x16x32_bf16 v[40:43], v[128:131], v[200:203], v[40:43]
	v_mfma_f32_16x16x32_bf16 v[32:35], v[136:139], v[200:203], v[32:35]
	v_mfma_f32_16x16x32_bf16 v[20:23], v[128:131], v[208:211], v[20:23]
	v_mfma_f32_16x16x32_bf16 v[16:19], v[136:139], v[208:211], v[16:19]
	s_setprio 0
	s_setprio 1
	v_mfma_f32_16x16x32_bf16 v[60:63], v[132:135], v[188:191], v[60:63]
	v_mfma_f32_16x16x32_bf16 v[56:59], v[140:143], v[188:191], v[56:59]
	v_mfma_f32_16x16x32_bf16 v[52:55], v[132:135], v[196:199], v[52:55]
	v_mfma_f32_16x16x32_bf16 v[48:51], v[140:143], v[196:199], v[48:51]
	s_setprio 0
	s_setprio 1
	v_mfma_f32_16x16x32_bf16 v[40:43], v[132:135], v[204:207], v[40:43]
	v_mfma_f32_16x16x32_bf16 v[32:35], v[140:143], v[204:207], v[32:35]
	v_mfma_f32_16x16x32_bf16 v[20:23], v[132:135], v[216:219], v[20:23]
	v_mfma_f32_16x16x32_bf16 v[16:19], v[140:143], v[216:219], v[16:19]
	s_setprio 0
	s_setprio 1
	v_mfma_f32_16x16x32_bf16 v[44:47], v[144:147], v[176:179], v[44:47]
	v_mfma_f32_16x16x32_bf16 v[36:39], v[168:171], v[176:179], v[36:39]
	v_mfma_f32_16x16x32_bf16 v[28:31], v[144:147], v[192:195], v[28:31]
	v_mfma_f32_16x16x32_bf16 v[24:27], v[168:171], v[192:195], v[24:27]
	s_setprio 0
	s_setprio 1
	v_mfma_f32_16x16x32_bf16 v[12:15], v[144:147], v[200:203], v[12:15]
	v_mfma_f32_16x16x32_bf16 v[8:11], v[168:171], v[200:203], v[8:11]
	v_mfma_f32_16x16x32_bf16 v[4:7], v[144:147], v[208:211], v[4:7]
	v_mfma_f32_16x16x32_bf16 v[0:3], v[168:171], v[208:211], v[0:3]
	s_setprio 0
	s_setprio 1
	v_mfma_f32_16x16x32_bf16 v[44:47], v[164:167], v[188:191], v[44:47]
	v_mfma_f32_16x16x32_bf16 v[36:39], v[172:175], v[188:191], v[36:39]
	v_mfma_f32_16x16x32_bf16 v[28:31], v[164:167], v[196:199], v[28:31]
	v_mfma_f32_16x16x32_bf16 v[24:27], v[172:175], v[196:199], v[24:27]
	s_setprio 0
	s_setprio 1
	v_mfma_f32_16x16x32_bf16 v[12:15], v[164:167], v[204:207], v[12:15]
	v_mfma_f32_16x16x32_bf16 v[8:11], v[172:175], v[204:207], v[8:11]
	v_mfma_f32_16x16x32_bf16 v[4:7], v[164:167], v[216:219], v[4:7]
	v_mfma_f32_16x16x32_bf16 v[0:3], v[172:175], v[216:219], v[0:3]
	s_setprio 0
	s_barrier
	s_add_i32 s44, s44, 2
	s_add_u32 s18, s18, 0x100
	s_addc_u32 s19, s19, 0
	s_add_u32 s42, s42, 0x100
	s_addc_u32 s43, s43, 0
	s_cmp_gt_u32 s44, 13
	s_cbranch_scc0 .LBB0_1243
	s_and_b64 vcc, exec, s[8:9]
	s_cbranch_vccz .LBB0_1246
	s_barrier

.LBB0_1325:
	ds_read_b128 v[120:123], v209
	ds_read_b128 v[128:131], v209 offset:1024
	ds_read_b128 v[136:139], v209 offset:2048
	ds_read_b128 v[140:143], v209 offset:3072
	ds_read_b128 v[144:147], v210
	ds_read_b128 v[148:151], v210 offset:1024
	ds_read_b128 v[152:155], v210 offset:2048
	ds_read_b128 v[156:159], v210 offset:3072
	s_add_u32 s4, s22, 0x100
	s_addc_u32 s5, s23, 0
	s_cmp_eq_u32 s47, 40
	s_cselect_b32 s27, s17, s5
	s_cselect_b32 s26, s16, s4
	s_cselect_b32 s25, s19, s46
	s_cselect_b32 s24, s18, s21
	v_lshl_add_u64 v[220:221], s[22:23], 0, v[176:177]
	s_add_i32 m0, s29, 0xc000
	ds_read_b128 v[160:163], v211
	ds_read_b128 v[164:167], v211 offset:1024
	ds_read_b128 v[184:187], v211 offset:2048
	ds_read_b128 v[188:191], v211 offset:3072
	ds_read_b128 v[192:195], v211 offset:4096
	ds_read_b128 v[196:199], v211 offset:5120
	ds_read_b128 v[200:203], v211 offset:6144
	ds_read_b128 v[216:219], v211 offset:7168
	global_load_lds_dwordx4 v[220:221], off
	v_lshl_add_u64 v[220:221], s[22:23], 0, v[178:179]
	s_add_i32 m0, s29, 0xe000
	s_nop 0
	global_load_lds_dwordx4 v[220:221], off
	s_waitcnt vmcnt(8)
	s_waitcnt lgkmcnt(0)
	s_barrier
	s_setprio 1
	s_waitcnt lgkmcnt(0)
	v_mfma_f32_16x16x32_bf16 v[132:135], v[120:123], v[160:163], v[132:135]
	v_mfma_f32_16x16x32_bf16 v[124:127], v[136:139], v[160:163], v[124:127]
	v_mfma_f32_16x16x32_bf16 v[108:111], v[120:123], v[184:187], v[108:111]
	v_mfma_f32_16x16x32_bf16 v[104:107], v[136:139], v[184:187], v[104:107]
	s_setprio 0
	s_setprio 1
	v_mfma_f32_16x16x32_bf16 v[92:95], v[120:123], v[192:195], v[92:95]
	v_mfma_f32_16x16x32_bf16 v[88:91], v[136:139], v[192:195], v[88:91]
	v_mfma_f32_16x16x32_bf16 v[76:79], v[120:123], v[200:203], v[76:79]
	v_mfma_f32_16x16x32_bf16 v[72:75], v[136:139], v[200:203], v[72:75]
	s_setprio 0
	s_setprio 1
	v_mfma_f32_16x16x32_bf16 v[132:135], v[128:131], v[164:167], v[132:135]
	v_mfma_f32_16x16x32_bf16 v[124:127], v[140:143], v[164:167], v[124:127]
	v_mfma_f32_16x16x32_bf16 v[108:111], v[128:131], v[188:191], v[108:111]
	v_mfma_f32_16x16x32_bf16 v[104:107], v[140:143], v[188:191], v[104:107]
	s_setprio 0
	s_setprio 1
	v_mfma_f32_16x16x32_bf16 v[92:95], v[128:131], v[196:199], v[92:95]
	v_mfma_f32_16x16x32_bf16 v[88:91], v[140:143], v[196:199], v[88:91]
	v_mfma_f32_16x16x32_bf16 v[76:79], v[128:131], v[216:219], v[76:79]
	v_mfma_f32_16x16x32_bf16 v[72:75], v[140:143], v[216:219], v[72:75]
	s_setprio 0
	s_setprio 1
	v_mfma_f32_16x16x32_bf16 v[116:119], v[144:147], v[160:163], v[116:119]
	v_mfma_f32_16x16x32_bf16 v[112:115], v[152:155], v[160:163], v[112:115]
	v_mfma_f32_16x16x32_bf16 v[100:103], v[144:147], v[184:187], v[100:103]
	v_mfma_f32_16x16x32_bf16 v[96:99], v[152:155], v[184:187], v[96:99]
	s_setprio 0
	s_setprio 1
	v_mfma_f32_16x16x32_bf16 v[84:87], v[144:147], v[192:195], v[84:87]
	v_mfma_f32_16x16x32_bf16 v[80:83], v[152:155], v[192:195], v[80:83]
	v_mfma_f32_16x16x32_bf16 v[68:71], v[144:147], v[200:203], v[68:71]
	v_mfma_f32_16x16x32_bf16 v[64:67], v[152:155], v[200:203], v[64:67]
	s_setprio 0
	s_setprio 1
	v_mfma_f32_16x16x32_bf16 v[116:119], v[148:151], v[164:167], v[116:119]
	v_mfma_f32_16x16x32_bf16 v[112:115], v[156:159], v[164:167], v[112:115]
	v_mfma_f32_16x16x32_bf16 v[100:103], v[148:151], v[188:191], v[100:103]
	v_mfma_f32_16x16x32_bf16 v[96:99], v[156:159], v[188:191], v[96:99]
	s_setprio 0
	s_setprio 1
	v_mfma_f32_16x16x32_bf16 v[84:87], v[148:151], v[196:199], v[84:87]
	v_mfma_f32_16x16x32_bf16 v[80:83], v[156:159], v[196:199], v[80:83]
	v_mfma_f32_16x16x32_bf16 v[68:71], v[148:151], v[216:219], v[68:71]
	v_mfma_f32_16x16x32_bf16 v[64:67], v[156:159], v[216:219], v[64:67]
	s_setprio 0
	s_barrier
	s_add_i32 s22, s41, s28
	v_lshl_add_u64 v[220:221], s[24:25], 0, v[170:171]
	s_mov_b32 m0, s22
	ds_read_b128 v[160:163], v211 offset:16384
	ds_read_b128 v[164:167], v211 offset:17408
	ds_read_b128 v[184:187], v211 offset:18432
	ds_read_b128 v[188:191], v211 offset:19456
	ds_read_b128 v[192:195], v211 offset:20480
	ds_read_b128 v[196:199], v211 offset:21504
	ds_read_b128 v[200:203], v211 offset:22528
	ds_read_b128 v[216:219], v211 offset:23552
	global_load_lds_dwordx4 v[220:221], off
	s_add_i32 m0, s22, 0x2000
	s_add_u32 s22, s24, 0xb0000
	v_lshl_add_u64 v[222:223], s[24:25], 0, v[174:175]
	s_addc_u32 s23, s25, 0
	s_add_i32 s48, s42, s28
	global_load_lds_dwordx4 v[222:223], off
	v_lshl_add_u64 v[224:225], s[22:23], 0, v[170:171]
	s_mov_b32 m0, s48
	v_lshl_add_u64 v[226:227], s[26:27], 0, v[172:173]
	global_load_lds_dwordx4 v[224:225], off
	v_lshl_add_u64 v[224:225], s[22:23], 0, v[174:175]
	s_add_i32 m0, s48, 0x2000
	s_nop 0
	global_load_lds_dwordx4 v[224:225], off
	v_lshl_add_u64 v[224:225], s[26:27], 0, v[168:169]
	s_mov_b32 m0, s29
	s_nop 0
	global_load_lds_dwordx4 v[224:225], off
	s_mov_b32 m0, s30
	s_nop 0
	global_load_lds_dwordx4 v[226:227], off
	s_waitcnt vmcnt(8)
	s_waitcnt lgkmcnt(0)
	s_barrier
	s_setprio 1
	s_waitcnt lgkmcnt(0)
	v_mfma_f32_16x16x32_bf16 v[60:63], v[120:123], v[160:163], v[60:63]
	v_mfma_f32_16x16x32_bf16 v[56:59], v[136:139], v[160:163], v[56:59]
	v_mfma_f32_16x16x32_bf16 v[44:47], v[120:123], v[184:187], v[44:47]
	v_mfma_f32_16x16x32_bf16 v[40:43], v[136:139], v[184:187], v[40:43]
	s_setprio 0
	s_setprio 1
	v_mfma_f32_16x16x32_bf16 v[28:31], v[120:123], v[192:195], v[28:31]
	v_mfma_f32_16x16x32_bf16 v[24:27], v[136:139], v[192:195], v[24:27]
	v_mfma_f32_16x16x32_bf16 v[12:15], v[120:123], v[200:203], v[12:15]
	v_mfma_f32_16x16x32_bf16 v[8:11], v[136:139], v[200:203], v[8:11]
	s_setprio 0
	s_setprio 1
	v_mfma_f32_16x16x32_bf16 v[60:63], v[128:131], v[164:167], v[60:63]
	v_mfma_f32_16x16x32_bf16 v[56:59], v[140:143], v[164:167], v[56:59]
	v_mfma_f32_16x16x32_bf16 v[44:47], v[128:131], v[188:191], v[44:47]
	v_mfma_f32_16x16x32_bf16 v[40:43], v[140:143], v[188:191], v[40:43]
	s_setprio 0
	s_setprio 1
	v_mfma_f32_16x16x32_bf16 v[28:31], v[128:131], v[196:199], v[28:31]
	v_mfma_f32_16x16x32_bf16 v[24:27], v[140:143], v[196:199], v[24:27]
	v_mfma_f32_16x16x32_bf16 v[12:15], v[128:131], v[216:219], v[12:15]
	v_mfma_f32_16x16x32_bf16 v[8:11], v[140:143], v[216:219], v[8:11]
	s_setprio 0
	s_setprio 1
	v_mfma_f32_16x16x32_bf16 v[52:55], v[144:147], v[160:163], v[52:55]
	v_mfma_f32_16x16x32_bf16 v[48:51], v[152:155], v[160:163], v[48:51]
	v_mfma_f32_16x16x32_bf16 v[36:39], v[144:147], v[184:187], v[36:39]
	v_mfma_f32_16x16x32_bf16 v[32:35], v[152:155], v[184:187], v[32:35]
	s_setprio 0
	s_setprio 1
	v_mfma_f32_16x16x32_bf16 v[20:23], v[144:147], v[192:195], v[20:23]
	v_mfma_f32_16x16x32_bf16 v[16:19], v[152:155], v[192:195], v[16:19]
	v_mfma_f32_16x16x32_bf16 v[4:7], v[144:147], v[200:203], v[4:7]
	v_mfma_f32_16x16x32_bf16 v[0:3], v[152:155], v[200:203], v[0:3]
	s_setprio 0
	s_setprio 1
	v_mfma_f32_16x16x32_bf16 v[52:55], v[148:151], v[164:167], v[52:55]
	v_mfma_f32_16x16x32_bf16 v[48:51], v[156:159], v[164:167], v[48:51]
	v_mfma_f32_16x16x32_bf16 v[36:39], v[148:151], v[188:191], v[36:39]
	v_mfma_f32_16x16x32_bf16 v[32:35], v[156:159], v[188:191], v[32:35]
	s_setprio 0
	s_setprio 1
	v_mfma_f32_16x16x32_bf16 v[20:23], v[148:151], v[196:199], v[20:23]
	v_mfma_f32_16x16x32_bf16 v[16:19], v[156:159], v[196:199], v[16:19]
	v_mfma_f32_16x16x32_bf16 v[4:7], v[148:151], v[216:219], v[4:7]
	v_mfma_f32_16x16x32_bf16 v[0:3], v[156:159], v[216:219], v[0:3]
	s_setprio 0
	s_barrier
	s_add_i32 s48, 0, 0x18000
	s_add_i32 s49, 0, 0x1c000
	v_add_u32_e32 v140, s48, v205
	v_add_u32_e32 v156, s49, v205
	ds_read_b128 v[120:123], v140
	ds_read_b128 v[128:131], v140 offset:1024
	ds_read_b128 v[136:139], v140 offset:2048
	ds_read_b128 v[140:143], v140 offset:3072
	ds_read_b128 v[144:147], v156
	ds_read_b128 v[148:151], v156 offset:1024
	ds_read_b128 v[152:155], v156 offset:2048
	ds_read_b128 v[156:159], v156 offset:3072
	s_add_u32 s22, s26, 0xb0000
	s_addc_u32 s23, s27, 0
	s_mov_b32 m0, s31
	v_lshl_add_u64 v[228:229], s[22:23], 0, v[168:169]
	ds_read_b128 v[160:163], v211 offset:32768
	ds_read_b128 v[164:167], v211 offset:33792
	ds_read_b128 v[184:187], v211 offset:34816
	ds_read_b128 v[188:191], v211 offset:35840
	ds_read_b128 v[192:195], v211 offset:36864
	ds_read_b128 v[196:199], v211 offset:37888
	ds_read_b128 v[200:203], v211 offset:38912
	ds_read_b128 v[216:219], v211 offset:39936
	global_load_lds_dwordx4 v[228:229], off
	v_lshl_add_u64 v[228:229], s[22:23], 0, v[172:173]
	s_mov_b32 m0, s33
	s_nop 0
	global_load_lds_dwordx4 v[228:229], off
	s_waitcnt vmcnt(8)
	s_waitcnt lgkmcnt(0)
	s_barrier
	s_setprio 1
	s_waitcnt lgkmcnt(0)
	v_mfma_f32_16x16x32_bf16 v[132:135], v[120:123], v[160:163], v[132:135]
	v_mfma_f32_16x16x32_bf16 v[124:127], v[136:139], v[160:163], v[124:127]
	v_mfma_f32_16x16x32_bf16 v[108:111], v[120:123], v[184:187], v[108:111]
	v_mfma_f32_16x16x32_bf16 v[104:107], v[136:139], v[184:187], v[104:107]
	s_setprio 0
	s_setprio 1
	v_mfma_f32_16x16x32_bf16 v[92:95], v[120:123], v[192:195], v[92:95]
	v_mfma_f32_16x16x32_bf16 v[88:91], v[136:139], v[192:195], v[88:91]
	v_mfma_f32_16x16x32_bf16 v[76:79], v[120:123], v[200:203], v[76:79]
	v_mfma_f32_16x16x32_bf16 v[72:75], v[136:139], v[200:203], v[72:75]
	s_setprio 0
	s_setprio 1
	v_mfma_f32_16x16x32_bf16 v[132:135], v[128:131], v[164:167], v[132:135]
	v_mfma_f32_16x16x32_bf16 v[124:127], v[140:143], v[164:167], v[124:127]
	v_mfma_f32_16x16x32_bf16 v[108:111], v[128:131], v[188:191], v[108:111]
	v_mfma_f32_16x16x32_bf16 v[104:107], v[140:143], v[188:191], v[104:107]
	s_setprio 0
	s_setprio 1
	v_mfma_f32_16x16x32_bf16 v[92:95], v[128:131], v[196:199], v[92:95]
	v_mfma_f32_16x16x32_bf16 v[88:91], v[140:143], v[196:199], v[88:91]
	v_mfma_f32_16x16x32_bf16 v[76:79], v[128:131], v[216:219], v[76:79]
	v_mfma_f32_16x16x32_bf16 v[72:75], v[140:143], v[216:219], v[72:75]
	s_setprio 0
	s_setprio 1
	v_mfma_f32_16x16x32_bf16 v[116:119], v[144:147], v[160:163], v[116:119]
	v_mfma_f32_16x16x32_bf16 v[112:115], v[152:155], v[160:163], v[112:115]
	v_mfma_f32_16x16x32_bf16 v[100:103], v[144:147], v[184:187], v[100:103]
	v_mfma_f32_16x16x32_bf16 v[96:99], v[152:155], v[184:187], v[96:99]
	s_setprio 0
	s_setprio 1
	v_mfma_f32_16x16x32_bf16 v[84:87], v[144:147], v[192:195], v[84:87]
	v_mfma_f32_16x16x32_bf16 v[80:83], v[152:155], v[192:195], v[80:83]
	v_mfma_f32_16x16x32_bf16 v[68:71], v[144:147], v[200:203], v[68:71]
	v_mfma_f32_16x16x32_bf16 v[64:67], v[152:155], v[200:203], v[64:67]
	s_setprio 0
	s_setprio 1
	v_mfma_f32_16x16x32_bf16 v[116:119], v[148:151], v[164:167], v[116:119]
	v_mfma_f32_16x16x32_bf16 v[112:115], v[156:159], v[164:167], v[112:115]
	v_mfma_f32_16x16x32_bf16 v[100:103], v[148:151], v[188:191], v[100:103]
	v_mfma_f32_16x16x32_bf16 v[96:99], v[156:159], v[188:191], v[96:99]
	s_setprio 0
	s_setprio 1
	v_mfma_f32_16x16x32_bf16 v[84:87], v[148:151], v[196:199], v[84:87]
	v_mfma_f32_16x16x32_bf16 v[80:83], v[156:159], v[196:199], v[80:83]
	v_mfma_f32_16x16x32_bf16 v[68:71], v[148:151], v[216:219], v[68:71]
	v_mfma_f32_16x16x32_bf16 v[64:67], v[156:159], v[216:219], v[64:67]
	s_setprio 0
	s_barrier
	s_add_i32 s22, s48, s28
	v_lshl_add_u64 v[220:221], v[220:221], 0, s[8:9]
	s_mov_b32 m0, s22
	ds_read_b128 v[160:163], v211 offset:49152
	ds_read_b128 v[164:167], v211 offset:50176
	ds_read_b128 v[184:187], v211 offset:51200
	ds_read_b128 v[188:191], v211 offset:52224
	ds_read_b128 v[192:195], v211 offset:53248
	ds_read_b128 v[196:199], v211 offset:54272
	ds_read_b128 v[200:203], v211 offset:55296
	ds_read_b128 v[216:219], v211 offset:56320
	global_load_lds_dwordx4 v[220:221], off
	s_add_i32 m0, s22, 0x2000
	s_add_u32 s22, s24, 0xb0080
	v_lshl_add_u64 v[220:221], v[222:223], 0, s[8:9]
	s_addc_u32 s23, s25, 0
	s_add_i32 s24, s49, s28
	global_load_lds_dwordx4 v[220:221], off
	v_lshl_add_u64 v[220:221], s[22:23], 0, v[170:171]
	s_mov_b32 m0, s24
	s_nop 0
	global_load_lds_dwordx4 v[220:221], off
	v_lshl_add_u64 v[220:221], s[22:23], 0, v[174:175]
	s_add_i32 m0, s24, 0x2000
	s_nop 0
	global_load_lds_dwordx4 v[220:221], off
	v_lshl_add_u64 v[220:221], v[224:225], 0, s[8:9]
	s_mov_b32 m0, s37
	s_nop 0
	global_load_lds_dwordx4 v[220:221], off
	v_lshl_add_u64 v[220:221], v[226:227], 0, s[8:9]
	s_mov_b32 m0, s38
	s_nop 0
	global_load_lds_dwordx4 v[220:221], off
	s_waitcnt vmcnt(8)
	s_waitcnt lgkmcnt(0)
	s_barrier
	s_setprio 1
	s_waitcnt lgkmcnt(0)
	v_mfma_f32_16x16x32_bf16 v[60:63], v[120:123], v[160:163], v[60:63]
	v_mfma_f32_16x16x32_bf16 v[56:59], v[136:139], v[160:163], v[56:59]
	v_mfma_f32_16x16x32_bf16 v[44:47], v[120:123], v[184:187], v[44:47]
	v_mfma_f32_16x16x32_bf16 v[40:43], v[136:139], v[184:187], v[40:43]
	s_setprio 0
	s_setprio 1
	v_mfma_f32_16x16x32_bf16 v[28:31], v[120:123], v[192:195], v[28:31]
	v_mfma_f32_16x16x32_bf16 v[24:27], v[136:139], v[192:195], v[24:27]
	v_mfma_f32_16x16x32_bf16 v[12:15], v[120:123], v[200:203], v[12:15]
	v_mfma_f32_16x16x32_bf16 v[8:11], v[136:139], v[200:203], v[8:11]
	s_setprio 0
	s_setprio 1
	v_mfma_f32_16x16x32_bf16 v[60:63], v[128:131], v[164:167], v[60:63]
	v_mfma_f32_16x16x32_bf16 v[56:59], v[140:143], v[164:167], v[56:59]
	v_mfma_f32_16x16x32_bf16 v[44:47], v[128:131], v[188:191], v[44:47]
	v_mfma_f32_16x16x32_bf16 v[40:43], v[140:143], v[188:191], v[40:43]
	s_setprio 0
	s_setprio 1
	v_mfma_f32_16x16x32_bf16 v[28:31], v[128:131], v[196:199], v[28:31]
	v_mfma_f32_16x16x32_bf16 v[24:27], v[140:143], v[196:199], v[24:27]
	v_mfma_f32_16x16x32_bf16 v[12:15], v[128:131], v[216:219], v[12:15]
	v_mfma_f32_16x16x32_bf16 v[8:11], v[140:143], v[216:219], v[8:11]
	s_setprio 0
	s_setprio 1
	v_mfma_f32_16x16x32_bf16 v[52:55], v[144:147], v[160:163], v[52:55]
	v_mfma_f32_16x16x32_bf16 v[48:51], v[152:155], v[160:163], v[48:51]
	v_mfma_f32_16x16x32_bf16 v[36:39], v[144:147], v[184:187], v[36:39]
	v_mfma_f32_16x16x32_bf16 v[32:35], v[152:155], v[184:187], v[32:35]
	s_setprio 0
	s_setprio 1
	v_mfma_f32_16x16x32_bf16 v[20:23], v[144:147], v[192:195], v[20:23]
	v_mfma_f32_16x16x32_bf16 v[16:19], v[152:155], v[192:195], v[16:19]
	v_mfma_f32_16x16x32_bf16 v[4:7], v[144:147], v[200:203], v[4:7]
	v_mfma_f32_16x16x32_bf16 v[0:3], v[152:155], v[200:203], v[0:3]
	s_setprio 0
	s_setprio 1
	v_mfma_f32_16x16x32_bf16 v[52:55], v[148:151], v[164:167], v[52:55]
	v_mfma_f32_16x16x32_bf16 v[48:51], v[156:159], v[164:167], v[48:51]
	v_mfma_f32_16x16x32_bf16 v[36:39], v[148:151], v[188:191], v[36:39]
	v_mfma_f32_16x16x32_bf16 v[32:35], v[156:159], v[188:191], v[32:35]
	s_setprio 0
	s_setprio 1
	v_mfma_f32_16x16x32_bf16 v[20:23], v[148:151], v[196:199], v[20:23]
	v_mfma_f32_16x16x32_bf16 v[16:19], v[156:159], v[196:199], v[16:19]
	v_mfma_f32_16x16x32_bf16 v[4:7], v[148:151], v[216:219], v[4:7]
	v_mfma_f32_16x16x32_bf16 v[0:3], v[156:159], v[216:219], v[0:3]
	s_setprio 0
	s_barrier
	s_add_i32 s47, s47, 2
	s_add_u32 s21, s21, 0x100
	s_addc_u32 s46, s46, 0
	s_cmp_gt_u32 s47, 41
	s_mov_b64 s[22:23], s[4:5]
	s_cbranch_scc0 .LBB0_1325
	s_and_b64 vcc, exec, s[10:11]
	s_cbranch_vccz .LBB0_1328
	s_barrier
